# final RMSNorm of the prompt rows fused into the phase-8 tile epilogue (per-row sum-of-squares partials exchanged between the 4 column-tile workgroups, y written directly); phase 9 only normalises the
# speedup vs baseline: 1.0006x; 1.0006x over previous
;     ...
;       if (NH > 0) {
;         const int per = KT / NH;
;         if (((kt + 1) % per) == 0) {
;           const int h = (kt + 1) / per - 1;
; #pragma unroll
;           for (int mf = 0; mf < 4; ++mf)
; #pragma unroll
;             for (int r = 0; r < 4; ++r) {
;               float s = rstdS[(wm * 64 + mf * 16 + 4 * g + r) * NH + h];
; #pragma unroll
;               for (int nf = 0; nf < 4; ++nf) {
;                 accT[mf][nf][r] += s * acc[mf][nf][r];
;                 acc[mf][nf][r] = 0.f;
;               }
;             }
;         }
.Lq3_205:
	v_add_u32_e32 v220, 12, v128
	ds_read_b32 v221, v220
	ds_read_b32 v223, v220 offset:256
	ds_read_b32 v225, v220 offset:512
	ds_read_b32 v227, v220 offset:768
	ds_read_b32 v229, v220 offset:2048
	ds_read_b32 v231, v220 offset:2304
	ds_read_b32 v233, v220 offset:2560
	ds_read_b32 v235, v220 offset:2816
	s_waitcnt lgkmcnt(0)
	s_nop 7
	v_mul_f32_e32 v120, v221, v120
	v_mul_f32_e32 v121, v221, v121
	v_mul_f32_e32 v122, v221, v122
	v_mul_f32_e32 v123, v221, v123
	v_mul_f32_e32 v124, v221, v124
	v_mul_f32_e32 v125, v221, v125
	v_mul_f32_e32 v126, v221, v126
	v_mul_f32_e32 v127, v221, v127
	v_mul_f32_e32 v112, v221, v112
	v_mul_f32_e32 v113, v221, v113
	v_mul_f32_e32 v114, v221, v114
	v_mul_f32_e32 v115, v221, v115
	v_mul_f32_e32 v116, v221, v116
	v_mul_f32_e32 v117, v221, v117
	v_mul_f32_e32 v118, v221, v118
	v_mul_f32_e32 v119, v221, v119
	v_mul_f32_e32 v104, v223, v104
	v_mul_f32_e32 v105, v223, v105
	v_mul_f32_e32 v106, v223, v106
	v_mul_f32_e32 v107, v223, v107
	v_mul_f32_e32 v108, v223, v108
	v_mul_f32_e32 v109, v223, v109
	v_mul_f32_e32 v110, v223, v110
	v_mul_f32_e32 v111, v223, v111
	v_mul_f32_e32 v96, v223, v96
	v_mul_f32_e32 v97, v223, v97
	v_mul_f32_e32 v98, v223, v98
	v_mul_f32_e32 v99, v223, v99
	v_mul_f32_e32 v100, v223, v100
	v_mul_f32_e32 v101, v223, v101
	v_mul_f32_e32 v102, v223, v102
	v_mul_f32_e32 v103, v223, v103
	v_mul_f32_e32 v88, v225, v88
	v_mul_f32_e32 v89, v225, v89
	v_mul_f32_e32 v90, v225, v90
	v_mul_f32_e32 v91, v225, v91
	v_mul_f32_e32 v92, v225, v92
	v_mul_f32_e32 v93, v225, v93
	v_mul_f32_e32 v94, v225, v94
	v_mul_f32_e32 v95, v225, v95
	v_mul_f32_e32 v80, v225, v80
	v_mul_f32_e32 v81, v225, v81
	v_mul_f32_e32 v82, v225, v82
	v_mul_f32_e32 v83, v225, v83
	v_mul_f32_e32 v84, v225, v84
	v_mul_f32_e32 v85, v225, v85
	v_mul_f32_e32 v86, v225, v86
	v_mul_f32_e32 v87, v225, v87
	v_mul_f32_e32 v72, v227, v72
	v_mul_f32_e32 v73, v227, v73
	v_mul_f32_e32 v74, v227, v74
	v_mul_f32_e32 v75, v227, v75
	v_mul_f32_e32 v76, v227, v76
	v_mul_f32_e32 v77, v227, v77
	v_mul_f32_e32 v78, v227, v78
	v_mul_f32_e32 v79, v227, v79
	v_mul_f32_e32 v64, v227, v64
	v_mul_f32_e32 v65, v227, v65
	v_mul_f32_e32 v66, v227, v66
	v_mul_f32_e32 v67, v227, v67
	v_mul_f32_e32 v68, v227, v68
	v_mul_f32_e32 v69, v227, v69
	v_mul_f32_e32 v70, v227, v70
	v_mul_f32_e32 v71, v227, v71
	v_mul_f32_e32 v56, v229, v56
	v_mul_f32_e32 v57, v229, v57
	v_mul_f32_e32 v58, v229, v58
	v_mul_f32_e32 v59, v229, v59
	v_mul_f32_e32 v60, v229, v60
	v_mul_f32_e32 v61, v229, v61
	v_mul_f32_e32 v62, v229, v62
	v_mul_f32_e32 v63, v229, v63
	v_mul_f32_e32 v48, v229, v48
	v_mul_f32_e32 v49, v229, v49
	v_mul_f32_e32 v50, v229, v50
	v_mul_f32_e32 v51, v229, v51
	v_mul_f32_e32 v52, v229, v52
	v_mul_f32_e32 v53, v229, v53
	v_mul_f32_e32 v54, v229, v54
	v_mul_f32_e32 v55, v229, v55
	v_mul_f32_e32 v40, v231, v40
	v_mul_f32_e32 v41, v231, v41
	v_mul_f32_e32 v42, v231, v42
	v_mul_f32_e32 v43, v231, v43
	v_mul_f32_e32 v44, v231, v44
	v_mul_f32_e32 v45, v231, v45
	v_mul_f32_e32 v46, v231, v46
	v_mul_f32_e32 v47, v231, v47
	v_mul_f32_e32 v32, v231, v32
	v_mul_f32_e32 v33, v231, v33
	v_mul_f32_e32 v34, v231, v34
	v_mul_f32_e32 v35, v231, v35
	v_mul_f32_e32 v36, v231, v36
	v_mul_f32_e32 v37, v231, v37
	v_mul_f32_e32 v38, v231, v38
	v_mul_f32_e32 v39, v231, v39
	v_mul_f32_e32 v24, v233, v24
	v_mul_f32_e32 v25, v233, v25
	v_mul_f32_e32 v26, v233, v26
	v_mul_f32_e32 v27, v233, v27
	v_mul_f32_e32 v28, v233, v28
	v_mul_f32_e32 v29, v233, v29
	v_mul_f32_e32 v30, v233, v30
	v_mul_f32_e32 v31, v233, v31
	v_mul_f32_e32 v16, v233, v16
	v_mul_f32_e32 v17, v233, v17
	v_mul_f32_e32 v18, v233, v18
	v_mul_f32_e32 v19, v233, v19
	v_mul_f32_e32 v20, v233, v20
	v_mul_f32_e32 v21, v233, v21
	v_mul_f32_e32 v22, v233, v22
	v_mul_f32_e32 v23, v233, v23
	v_mul_f32_e32 v8, v235, v8
	v_mul_f32_e32 v9, v235, v9
	v_mul_f32_e32 v10, v235, v10
	v_mul_f32_e32 v11, v235, v11
	v_mul_f32_e32 v12, v235, v12
	v_mul_f32_e32 v13, v235, v13
	v_mul_f32_e32 v14, v235, v14
	v_mul_f32_e32 v15, v235, v15
	v_mul_f32_e32 v0, v235, v0
	v_mul_f32_e32 v1, v235, v1
	v_mul_f32_e32 v2, v235, v2
	v_mul_f32_e32 v3, v235, v3
	v_mul_f32_e32 v4, v235, v4
	v_mul_f32_e32 v5, v235, v5
	v_mul_f32_e32 v6, v235, v6
	v_mul_f32_e32 v7, v235, v7
	s_barrier
;     ...
;       if (EPI == 1) {
; #pragma unroll
;         for (int r = 0; r < 4; ++r) {
;           const int row = m0 + wm * 64 + mf * 16 + 4 * g + r;
; #pragma unroll
;           for (int nf = 0; nf < 4; ++nf) {
;             const int col = n0 + wn * 64 + nf * 16 + l15;
;             rvv[r][nf] = resid ? resid[(size_t)row * 1024 + col] : xrow(p, row)[col];
;           }
;         }
;       }
; #pragma unroll
;       for (int r = 0; r < 4; ++r) {
;         const int row = m0 + wm * 64 + mf * 16 + 4 * g + r;
;         if (EPI == 0) {
;           u16* proj = (u16*)(p.ws + OFF_PROJ) + (size_t)row * PROJ_LD;
;           if (n0 < 2048) {
;             const float2* rope = (const float2*)(p.ws + OFF_ROPE);
;             const int pi = row < NPROMPT ? (row & 2047) : 2048 + ((row - NPROMPT) & 7);
; #pragma unroll
;             for (int np = 0; np < 2; ++np) {
;               const int pc = n0 + wn * 64 + np * 32;
;               const int i = ((pc & 255) >> 5) * 16 + l15;
;               const float2 cs = rope[pi * 128 + i];
;               const float x1 = acc[mf][2 * np][r], x2 = acc[mf][2 * np + 1][r];
;               float y1 = x1 * cs.x - x2 * cs.y, y2 = x1 * cs.y + x2 * cs.x;
;               if (pc >= 1024) { y1 *= 0.0625f; y2 *= 0.0625f; }
;               const int f1 = (pc & ~255) + i;
;               proj[f1] = f2bf(y1);
;               proj[f1 + 128] = f2bf(y2);
;             }
;           } else {
; #pragma unroll
;             for (int nf = 0; nf < 4; ++nf) proj[n0 + wn * 64 + nf * 16 + l15] = f2bf(acc[mf][nf][r]);
;           }
;         } else if (EPI == 1) {
; #pragma unroll
;           for (int nf = 0; nf < 4; ++nf) {
;             const int col = n0 + wn * 64 + nf * 16 + l15;
;             const float a = (NH > 0) ? accT[mf][nf][r] : acc[mf][nf][r];
;             outf[(size_t)row * 1024 + col] = rvv[r][nf] + a;
;           }
	v_readlane_b32 s4, v255, 51
	v_readlane_b32 s1, v255, 52
	v_readlane_b32 s5, v255, 6
	v_and_b32_e32 v176, 15, v195
	v_lshrrev_b32_e32 v177, 4, v195
	s_lshr_b32 s6, s5, 2
	s_and_b32 s7, s5, 3
	s_lshl_b32 s6, s6, 6
	v_add_u32_e32 v178, s6, v176
	v_mul_u32_u24_e32 v178, 0x410, v178
	s_lshl_b32 s7, s7, 7
	v_lshl_add_u32 v178, v177, 4, v178
	v_add_u32_e32 v178, s7, v178
	s_lshl_b32 s7, s5, 4
	v_lshlrev_b32_e32 v179, 4, v195
	s_mul_i32 s6, s7, 0x410
	v_add_u32_e32 v180, s6, v179
	s_lshl_b32 s26, s4, 8
	s_add_i32 s26, s26, s7
	s_lshl_b32 s4, s26, 12
	s_lshl_b32 s27, s1, 10
	s_add_i32 s4, s4, s27
	v_add_u32_e32 v181, s4, v179
	v_readlane_b32 s0, v255, 0
	v_readlane_b32 s1, v255, 1
	s_load_dwordx2 s[20:21], s[0:1], 0x0
	s_add_u32 s24, s84, 0x15aa2000
	s_addc_u32 s25, s85, 0
	s_waitcnt lgkmcnt(0)
	v_mov_b32_e32 v182, v181
	global_load_dwordx4 v[184:187], v182, s[20:21]
	v_add_u32_e32 v182, 0x1000, v182
	global_load_dwordx4 v[188:191], v182, s[20:21]
	v_add_u32_e32 v182, 0x1000, v182
	global_load_dwordx4 v[196:199], v182, s[20:21]
	v_add_u32_e32 v182, 0x1000, v182
	global_load_dwordx4 v[200:203], v182, s[20:21]
	v_add_u32_e32 v182, 0x1000, v182
	global_load_dwordx4 v[204:207], v182, s[20:21]
	v_add_u32_e32 v182, 0x1000, v182
	global_load_dwordx4 v[208:211], v182, s[20:21]
	v_add_u32_e32 v182, 0x1000, v182
	global_load_dwordx4 v[212:215], v182, s[20:21]
	v_add_u32_e32 v182, 0x1000, v182
	global_load_dwordx4 v[216:219], v182, s[20:21]
	v_add_u32_e32 v182, 0x1000, v182
	global_load_dwordx4 v[220:223], v182, s[20:21]
	v_add_u32_e32 v182, 0x1000, v182
	global_load_dwordx4 v[224:227], v182, s[20:21]
	v_add_u32_e32 v182, 0x1000, v182
	global_load_dwordx4 v[228:231], v182, s[20:21]
	v_add_u32_e32 v182, 0x1000, v182
	global_load_dwordx4 v[232:235], v182, s[20:21]
	v_add_u32_e32 v182, 0x1000, v182
	global_load_dwordx4 v[236:239], v182, s[20:21]
	v_add_u32_e32 v182, 0x1000, v182
	global_load_dwordx4 v[240:243], v182, s[20:21]
	v_add_u32_e32 v182, 0x1000, v182
	global_load_dwordx4 v[244:247], v182, s[20:21]
	v_add_u32_e32 v182, 0x1000, v182
	global_load_dwordx4 v[248:251], v182, s[20:21]
	ds_write_b128 v178, v[120:123]
	ds_write_b128 v178, v[124:127] offset:64
	ds_write_b128 v178, v[104:107] offset:16640
	ds_write_b128 v178, v[108:111] offset:16704
	ds_write_b128 v178, v[88:91] offset:33280
	ds_write_b128 v178, v[92:95] offset:33344
	ds_write_b128 v178, v[72:75] offset:49920
	ds_write_b128 v178, v[76:79] offset:49984
	ds_write_b128 v178, v[112:115] offset:512
	ds_write_b128 v178, v[116:119] offset:576
	ds_write_b128 v178, v[96:99] offset:17152
	ds_write_b128 v178, v[100:103] offset:17216
	ds_write_b128 v178, v[80:83] offset:33792
	ds_write_b128 v178, v[84:87] offset:33856
	ds_write_b128 v178, v[64:67] offset:50432
	ds_write_b128 v178, v[68:71] offset:50496
	s_waitcnt lgkmcnt(0)
	s_barrier
	ds_read_b128 v[64:67], v180
	ds_read_b128 v[68:71], v180 offset:1040
	ds_read_b128 v[72:75], v180 offset:2080
	ds_read_b128 v[76:79], v180 offset:3120
	ds_read_b128 v[80:83], v180 offset:4160
	ds_read_b128 v[84:87], v180 offset:5200
	ds_read_b128 v[88:91], v180 offset:6240
	ds_read_b128 v[92:95], v180 offset:7280
	ds_read_b128 v[96:99], v180 offset:8320
	ds_read_b128 v[100:103], v180 offset:9360
	ds_read_b128 v[104:107], v180 offset:10400
	ds_read_b128 v[108:111], v180 offset:11440
	ds_read_b128 v[112:115], v180 offset:12480
	ds_read_b128 v[116:119], v180 offset:13520
	ds_read_b128 v[120:123], v180 offset:14560
	ds_read_b128 v[124:127], v180 offset:15600
	s_waitcnt lgkmcnt(0)
	s_barrier
	v_mov_b32_e32 v182, v181
	s_waitcnt vmcnt(15)
	v_add_f32_e32 v64, v64, v184
	v_add_f32_e32 v65, v65, v185
	v_add_f32_e32 v66, v66, v186
	v_add_f32_e32 v67, v67, v187
	global_store_dwordx4 v182, v[64:67], s[24:25]
	v_add_u32_e32 v182, 0x1000, v182
	s_waitcnt vmcnt(15)
	v_add_f32_e32 v68, v68, v188
	v_add_f32_e32 v69, v69, v189
	v_add_f32_e32 v70, v70, v190
	v_add_f32_e32 v71, v71, v191
	global_store_dwordx4 v182, v[68:71], s[24:25]
	v_add_u32_e32 v182, 0x1000, v182
	s_waitcnt vmcnt(15)
	v_add_f32_e32 v72, v72, v196
	v_add_f32_e32 v73, v73, v197
	v_add_f32_e32 v74, v74, v198
	v_add_f32_e32 v75, v75, v199
	global_store_dwordx4 v182, v[72:75], s[24:25]
	v_add_u32_e32 v182, 0x1000, v182
	s_waitcnt vmcnt(15)
	v_add_f32_e32 v76, v76, v200
	v_add_f32_e32 v77, v77, v201
	v_add_f32_e32 v78, v78, v202
	v_add_f32_e32 v79, v79, v203
	global_store_dwordx4 v182, v[76:79], s[24:25]
	v_add_u32_e32 v182, 0x1000, v182
	s_waitcnt vmcnt(15)
	v_add_f32_e32 v80, v80, v204
	v_add_f32_e32 v81, v81, v205
	v_add_f32_e32 v82, v82, v206
	v_add_f32_e32 v83, v83, v207
	global_store_dwordx4 v182, v[80:83], s[24:25]
	v_add_u32_e32 v182, 0x1000, v182
	s_waitcnt vmcnt(15)
	v_add_f32_e32 v84, v84, v208
	v_add_f32_e32 v85, v85, v209
	v_add_f32_e32 v86, v86, v210
	v_add_f32_e32 v87, v87, v211
	global_store_dwordx4 v182, v[84:87], s[24:25]
	v_add_u32_e32 v182, 0x1000, v182
	s_waitcnt vmcnt(15)
	v_add_f32_e32 v88, v88, v212
	v_add_f32_e32 v89, v89, v213
	v_add_f32_e32 v90, v90, v214
	v_add_f32_e32 v91, v91, v215
	global_store_dwordx4 v182, v[88:91], s[24:25]
	v_add_u32_e32 v182, 0x1000, v182
	s_waitcnt vmcnt(15)
	v_add_f32_e32 v92, v92, v216
	v_add_f32_e32 v93, v93, v217
	v_add_f32_e32 v94, v94, v218
	v_add_f32_e32 v95, v95, v219
	global_store_dwordx4 v182, v[92:95], s[24:25]
	v_add_u32_e32 v182, 0x1000, v182
	s_waitcnt vmcnt(15)
	v_add_f32_e32 v96, v96, v220
	v_add_f32_e32 v97, v97, v221
	v_add_f32_e32 v98, v98, v222
	v_add_f32_e32 v99, v99, v223
	global_store_dwordx4 v182, v[96:99], s[24:25]
	v_add_u32_e32 v182, 0x1000, v182
	s_waitcnt vmcnt(15)
;     ...
;       if (EPI == 1) {
; #pragma unroll
;         for (int r = 0; r < 4; ++r) {
;           const int row = m0 + wm * 64 + mf * 16 + 4 * g + r;
; #pragma unroll
;           for (int nf = 0; nf < 4; ++nf) {
;             const int col = n0 + wn * 64 + nf * 16 + l15;
;             rvv[r][nf] = resid ? resid[(size_t)row * 1024 + col] : xrow(p, row)[col];
;           }
;         }
;       }
; #pragma unroll
;       for (int r = 0; r < 4; ++r) {
;         const int row = m0 + wm * 64 + mf * 16 + 4 * g + r;
;         if (EPI == 0) {
;           u16* proj = (u16*)(p.ws + OFF_PROJ) + (size_t)row * PROJ_LD;
;           if (n0 < 2048) {
;             const float2* rope = (const float2*)(p.ws + OFF_ROPE);
;             const int pi = row < NPROMPT ? (row & 2047) : 2048 + ((row - NPROMPT) & 7);
; #pragma unroll
;             for (int np = 0; np < 2; ++np) {
;               const int pc = n0 + wn * 64 + np * 32;
;               const int i = ((pc & 255) >> 5) * 16 + l15;
;               const float2 cs = rope[pi * 128 + i];
;               const float x1 = acc[mf][2 * np][r], x2 = acc[mf][2 * np + 1][r];
;               float y1 = x1 * cs.x - x2 * cs.y, y2 = x1 * cs.y + x2 * cs.x;
;               if (pc >= 1024) { y1 *= 0.0625f; y2 *= 0.0625f; }
;               const int f1 = (pc & ~255) + i;
;               proj[f1] = f2bf(y1);
;               proj[f1 + 128] = f2bf(y2);
;             }
;           } else {
; #pragma unroll
;             for (int nf = 0; nf < 4; ++nf) proj[n0 + wn * 64 + nf * 16 + l15] = f2bf(acc[mf][nf][r]);
;           }
;         } else if (EPI == 1) {
; #pragma unroll
;           for (int nf = 0; nf < 4; ++nf) {
;             const int col = n0 + wn * 64 + nf * 16 + l15;
;             const float a = (NH > 0) ? accT[mf][nf][r] : acc[mf][nf][r];
;             outf[(size_t)row * 1024 + col] = rvv[r][nf] + a;
;           }
	v_add_f32_e32 v100, v100, v224
	v_add_f32_e32 v101, v101, v225
	v_add_f32_e32 v102, v102, v226
	v_add_f32_e32 v103, v103, v227
	global_store_dwordx4 v182, v[100:103], s[24:25]
	v_add_u32_e32 v182, 0x1000, v182
	s_waitcnt vmcnt(15)
	v_add_f32_e32 v104, v104, v228
	v_add_f32_e32 v105, v105, v229
	v_add_f32_e32 v106, v106, v230
	v_add_f32_e32 v107, v107, v231
	global_store_dwordx4 v182, v[104:107], s[24:25]
	v_add_u32_e32 v182, 0x1000, v182
	s_waitcnt vmcnt(15)
	v_add_f32_e32 v108, v108, v232
	v_add_f32_e32 v109, v109, v233
	v_add_f32_e32 v110, v110, v234
	v_add_f32_e32 v111, v111, v235
	global_store_dwordx4 v182, v[108:111], s[24:25]
	v_add_u32_e32 v182, 0x1000, v182
	s_waitcnt vmcnt(15)
	v_add_f32_e32 v112, v112, v236
	v_add_f32_e32 v113, v113, v237
	v_add_f32_e32 v114, v114, v238
	v_add_f32_e32 v115, v115, v239
	global_store_dwordx4 v182, v[112:115], s[24:25]
	v_add_u32_e32 v182, 0x1000, v182
	s_waitcnt vmcnt(15)
	v_add_f32_e32 v116, v116, v240
	v_add_f32_e32 v117, v117, v241
	v_add_f32_e32 v118, v118, v242
	v_add_f32_e32 v119, v119, v243
	global_store_dwordx4 v182, v[116:119], s[24:25]
	v_add_u32_e32 v182, 0x1000, v182
	s_waitcnt vmcnt(15)
	v_add_f32_e32 v120, v120, v244
	v_add_f32_e32 v121, v121, v245
	v_add_f32_e32 v122, v122, v246
	v_add_f32_e32 v123, v123, v247
	global_store_dwordx4 v182, v[120:123], s[24:25]
	v_add_u32_e32 v182, 0x1000, v182
	s_waitcnt vmcnt(15)
	v_add_f32_e32 v124, v124, v248
	v_add_f32_e32 v125, v125, v249
	v_add_f32_e32 v126, v126, v250
	v_add_f32_e32 v127, v127, v251
	global_store_dwordx4 v182, v[124:127], s[24:25]
	v_add_u32_e32 v181, 0x80000, v181
	v_mov_b32_e32 v182, v181
	global_load_dwordx4 v[184:187], v182, s[20:21]
	v_add_u32_e32 v182, 0x1000, v182
	global_load_dwordx4 v[188:191], v182, s[20:21]
	v_add_u32_e32 v182, 0x1000, v182
	global_load_dwordx4 v[196:199], v182, s[20:21]
	v_add_u32_e32 v182, 0x1000, v182
	global_load_dwordx4 v[200:203], v182, s[20:21]
	v_add_u32_e32 v182, 0x1000, v182
	global_load_dwordx4 v[204:207], v182, s[20:21]
	v_add_u32_e32 v182, 0x1000, v182
	global_load_dwordx4 v[208:211], v182, s[20:21]
	v_add_u32_e32 v182, 0x1000, v182
	global_load_dwordx4 v[212:215], v182, s[20:21]
	v_add_u32_e32 v182, 0x1000, v182
	global_load_dwordx4 v[216:219], v182, s[20:21]
	v_add_u32_e32 v182, 0x1000, v182
	global_load_dwordx4 v[220:223], v182, s[20:21]
	v_add_u32_e32 v182, 0x1000, v182
	global_load_dwordx4 v[224:227], v182, s[20:21]
	v_add_u32_e32 v182, 0x1000, v182
	global_load_dwordx4 v[228:231], v182, s[20:21]
	v_add_u32_e32 v182, 0x1000, v182
	global_load_dwordx4 v[232:235], v182, s[20:21]
	v_add_u32_e32 v182, 0x1000, v182
	global_load_dwordx4 v[236:239], v182, s[20:21]
	v_add_u32_e32 v182, 0x1000, v182
	global_load_dwordx4 v[240:243], v182, s[20:21]
	v_add_u32_e32 v182, 0x1000, v182
	global_load_dwordx4 v[244:247], v182, s[20:21]
	v_add_u32_e32 v182, 0x1000, v182
	global_load_dwordx4 v[248:251], v182, s[20:21]
	ds_write_b128 v178, v[56:59]
	ds_write_b128 v178, v[60:63] offset:64
	ds_write_b128 v178, v[40:43] offset:16640
	ds_write_b128 v178, v[44:47] offset:16704
	ds_write_b128 v178, v[24:27] offset:33280
	ds_write_b128 v178, v[28:31] offset:33344
	ds_write_b128 v178, v[8:11] offset:49920
	ds_write_b128 v178, v[12:15] offset:49984
	ds_write_b128 v178, v[48:51] offset:512
	ds_write_b128 v178, v[52:55] offset:576
	ds_write_b128 v178, v[32:35] offset:17152
	ds_write_b128 v178, v[36:39] offset:17216
	ds_write_b128 v178, v[16:19] offset:33792
	ds_write_b128 v178, v[20:23] offset:33856
	ds_write_b128 v178, v[0:3] offset:50432
	ds_write_b128 v178, v[4:7] offset:50496
	s_waitcnt lgkmcnt(0)
	s_barrier
	ds_read_b128 v[64:67], v180
	ds_read_b128 v[68:71], v180 offset:1040
	ds_read_b128 v[72:75], v180 offset:2080
	ds_read_b128 v[76:79], v180 offset:3120
	ds_read_b128 v[80:83], v180 offset:4160
	ds_read_b128 v[84:87], v180 offset:5200
	ds_read_b128 v[88:91], v180 offset:6240
	ds_read_b128 v[92:95], v180 offset:7280
	ds_read_b128 v[96:99], v180 offset:8320
	ds_read_b128 v[100:103], v180 offset:9360
	ds_read_b128 v[104:107], v180 offset:10400
	ds_read_b128 v[108:111], v180 offset:11440
	ds_read_b128 v[112:115], v180 offset:12480
	ds_read_b128 v[116:119], v180 offset:13520
	ds_read_b128 v[120:123], v180 offset:14560
	ds_read_b128 v[124:127], v180 offset:15600
	s_waitcnt lgkmcnt(0)
	s_barrier
;     ...
;         } else if (EPI == 1) {
; #pragma unroll
;           for (int nf = 0; nf < 4; ++nf) {
;             const int col = n0 + wn * 64 + nf * 16 + l15;
;             const float a = (NH > 0) ? accT[mf][nf][r] : acc[mf][nf][r];
;             outf[(size_t)row * 1024 + col] = rvv[r][nf] + a;
;           }
; template <int NH>
; __device__ void gemm_sample_rows(const Params& p, const u16* __restrict__ A, const u16* __restrict__ Bt,
;                                  const float* __restrict__ resid, float* __restrict__ outf, unsigned char* smem, const int rep) {
;   constexpr int K = 2048, RS = 65;
;   float* red = (float*)smem;
;   float* rstdS = red + 8 * 64 * RS;
;   const int tid = (int)p.tidx, lane = tid & 63, w = (int)p.wv, l15 = lane & 15, g = lane >> 4;
;   const float* parts = (const float*)(p.ws + OFF_PARTS);
;   for (int item0 = blockIdx.x; item0 < 256 * rep; item0 += gridDim.x) {
;     const int item = item0 & 255;
;     const int m0 = NPROMPT + (item >> 4) * 64, n0 = (item & 15) * 64;
;     for (int idx = tid; idx < 64 * NH; idx += NTHR) {
	v_mov_b32_e32 v182, v181
	s_waitcnt vmcnt(15)
	v_add_f32_e32 v64, v64, v184
	v_add_f32_e32 v65, v65, v185
	v_add_f32_e32 v66, v66, v186
	v_add_f32_e32 v67, v67, v187
	global_store_dwordx4 v182, v[64:67], s[24:25]
	v_add_u32_e32 v182, 0x1000, v182
	s_waitcnt vmcnt(15)
	v_add_f32_e32 v68, v68, v188
	v_add_f32_e32 v69, v69, v189
	v_add_f32_e32 v70, v70, v190
	v_add_f32_e32 v71, v71, v191
	global_store_dwordx4 v182, v[68:71], s[24:25]
	v_add_u32_e32 v182, 0x1000, v182
	s_waitcnt vmcnt(15)
	v_add_f32_e32 v72, v72, v196
	v_add_f32_e32 v73, v73, v197
	v_add_f32_e32 v74, v74, v198
	v_add_f32_e32 v75, v75, v199
	global_store_dwordx4 v182, v[72:75], s[24:25]
	v_add_u32_e32 v182, 0x1000, v182
	s_waitcnt vmcnt(15)
	v_add_f32_e32 v76, v76, v200
	v_add_f32_e32 v77, v77, v201
	v_add_f32_e32 v78, v78, v202
	v_add_f32_e32 v79, v79, v203
	global_store_dwordx4 v182, v[76:79], s[24:25]
	v_add_u32_e32 v182, 0x1000, v182
	s_waitcnt vmcnt(15)
	v_add_f32_e32 v80, v80, v204
	v_add_f32_e32 v81, v81, v205
	v_add_f32_e32 v82, v82, v206
	v_add_f32_e32 v83, v83, v207
	global_store_dwordx4 v182, v[80:83], s[24:25]
	v_add_u32_e32 v182, 0x1000, v182
	s_waitcnt vmcnt(15)
	v_add_f32_e32 v84, v84, v208
	v_add_f32_e32 v85, v85, v209
	v_add_f32_e32 v86, v86, v210
	v_add_f32_e32 v87, v87, v211
	global_store_dwordx4 v182, v[84:87], s[24:25]
	v_add_u32_e32 v182, 0x1000, v182
	s_waitcnt vmcnt(15)
	v_add_f32_e32 v88, v88, v212
	v_add_f32_e32 v89, v89, v213
	v_add_f32_e32 v90, v90, v214
	v_add_f32_e32 v91, v91, v215
	global_store_dwordx4 v182, v[88:91], s[24:25]
	v_add_u32_e32 v182, 0x1000, v182
	s_waitcnt vmcnt(15)
	v_add_f32_e32 v92, v92, v216
	v_add_f32_e32 v93, v93, v217
	v_add_f32_e32 v94, v94, v218
	v_add_f32_e32 v95, v95, v219
	global_store_dwordx4 v182, v[92:95], s[24:25]
	v_add_u32_e32 v182, 0x1000, v182
	s_waitcnt vmcnt(15)
	v_add_f32_e32 v96, v96, v220
	v_add_f32_e32 v97, v97, v221
	v_add_f32_e32 v98, v98, v222
	v_add_f32_e32 v99, v99, v223
	global_store_dwordx4 v182, v[96:99], s[24:25]
	v_add_u32_e32 v182, 0x1000, v182
	s_waitcnt vmcnt(15)
	v_add_f32_e32 v100, v100, v224
	v_add_f32_e32 v101, v101, v225
	v_add_f32_e32 v102, v102, v226
	v_add_f32_e32 v103, v103, v227
	global_store_dwordx4 v182, v[100:103], s[24:25]
	v_add_u32_e32 v182, 0x1000, v182
	s_waitcnt vmcnt(15)
	v_add_f32_e32 v104, v104, v228
	v_add_f32_e32 v105, v105, v229
	v_add_f32_e32 v106, v106, v230
	v_add_f32_e32 v107, v107, v231
	global_store_dwordx4 v182, v[104:107], s[24:25]
	v_add_u32_e32 v182, 0x1000, v182
	s_waitcnt vmcnt(15)
	v_add_f32_e32 v108, v108, v232
	v_add_f32_e32 v109, v109, v233
	v_add_f32_e32 v110, v110, v234
	v_add_f32_e32 v111, v111, v235
	global_store_dwordx4 v182, v[108:111], s[24:25]
	v_add_u32_e32 v182, 0x1000, v182
	s_waitcnt vmcnt(15)
	v_add_f32_e32 v112, v112, v236
	v_add_f32_e32 v113, v113, v237
	v_add_f32_e32 v114, v114, v238
	v_add_f32_e32 v115, v115, v239
	global_store_dwordx4 v182, v[112:115], s[24:25]
	v_add_u32_e32 v182, 0x1000, v182
	s_waitcnt vmcnt(15)
	v_add_f32_e32 v116, v116, v240
	v_add_f32_e32 v117, v117, v241
	v_add_f32_e32 v118, v118, v242
	v_add_f32_e32 v119, v119, v243
	global_store_dwordx4 v182, v[116:119], s[24:25]
	v_add_u32_e32 v182, 0x1000, v182
	s_waitcnt vmcnt(15)
	v_add_f32_e32 v120, v120, v244
	v_add_f32_e32 v121, v121, v245
	v_add_f32_e32 v122, v122, v246
	v_add_f32_e32 v123, v123, v247
	global_store_dwordx4 v182, v[120:123], s[24:25]
	v_add_u32_e32 v182, 0x1000, v182
	s_waitcnt vmcnt(15)
	v_add_f32_e32 v124, v124, v248
	v_add_f32_e32 v125, v125, v249
	v_add_f32_e32 v126, v126, v250
	v_add_f32_e32 v127, v127, v251
	global_store_dwordx4 v182, v[124:127], s[24:25]
	s_waitcnt vmcnt(0)
	s_barrier
	v_readlane_b32 s0, v255, 0
	v_readlane_b32 s1, v255, 1
	s_load_dwordx4 s[8:11], s[0:1], 0x0
	s_mov_b64 s[0:1], 0
	s_add_u32 s14, s84, s0
	s_addc_u32 s15, s85, s1
	v_readlane_b32 s23, v255, 6
	s_bfe_u32 s24, s90, 0x10003
	s_lshl_b32 s22, s23, 6
	s_add_i32 s24, s24, 1
	s_add_u32 s6, s14, 0x15aa2000
	s_addc_u32 s7, s15, 0
	s_waitcnt vmcnt(1)
	v_mbcnt_lo_u32_b32 v0, -1, 0
	s_add_u32 s12, s14, 0x15662000
	v_mbcnt_hi_u32_b32 v195, -1, v0
	s_addc_u32 s13, s15, 0
	s_lshl_b32 s25, s24, 9
	s_mov_b32 s25, 0
	s_mov_b64 s[2:3], 0
	v_add_u32_e32 v196, s22, v195
	s_cmp_lt_i32 s78, s25
	v_and_b32_e32 v181, 15, v195
	s_cbranch_scc1 .LBB0_703
	v_and_b32_e32 v0, 15, v195
	s_branch .LBB0_704

;     ...
;       if (NH > 0) {
;         const int per = KT / NH;
;         if (((kt + 1) % per) == 0) {
;           const int h = (kt + 1) / per - 1;
; #pragma unroll
;           for (int mf = 0; mf < 4; ++mf)
; #pragma unroll
;             for (int r = 0; r < 4; ++r) {
;               float s = rstdS[(wm * 64 + mf * 16 + 4 * g + r) * NH + h];
; #pragma unroll
;               for (int nf = 0; nf < 4; ++nf) {
;                 accT[mf][nf][r] += s * acc[mf][nf][r];
;                 acc[mf][nf][r] = 0.f;
;               }
;             }
;         }
.Lq8_205:
	v_add_u32_e32 v220, 28, v128
	ds_read_b32 v221, v220
	ds_read_b32 v223, v220 offset:512
	ds_read_b32 v225, v220 offset:1024
	ds_read_b32 v227, v220 offset:1536
	ds_read_b32 v229, v220 offset:4096
	ds_read_b32 v231, v220 offset:4608
	ds_read_b32 v233, v220 offset:5120
	ds_read_b32 v235, v220 offset:5632
	s_waitcnt lgkmcnt(0)
	s_nop 7
	v_mul_f32_e32 v120, v221, v120
	v_mul_f32_e32 v121, v221, v121
	v_mul_f32_e32 v122, v221, v122
	v_mul_f32_e32 v123, v221, v123
	v_mul_f32_e32 v124, v221, v124
	v_mul_f32_e32 v125, v221, v125
	v_mul_f32_e32 v126, v221, v126
	v_mul_f32_e32 v127, v221, v127
	v_mul_f32_e32 v112, v221, v112
	v_mul_f32_e32 v113, v221, v113
	v_mul_f32_e32 v114, v221, v114
	v_mul_f32_e32 v115, v221, v115
	v_mul_f32_e32 v116, v221, v116
	v_mul_f32_e32 v117, v221, v117
	v_mul_f32_e32 v118, v221, v118
	v_mul_f32_e32 v119, v221, v119
	v_mul_f32_e32 v104, v223, v104
	v_mul_f32_e32 v105, v223, v105
	v_mul_f32_e32 v106, v223, v106
	v_mul_f32_e32 v107, v223, v107
	v_mul_f32_e32 v108, v223, v108
	v_mul_f32_e32 v109, v223, v109
	v_mul_f32_e32 v110, v223, v110
	v_mul_f32_e32 v111, v223, v111
	v_mul_f32_e32 v96, v223, v96
	v_mul_f32_e32 v97, v223, v97
	v_mul_f32_e32 v98, v223, v98
	v_mul_f32_e32 v99, v223, v99
	v_mul_f32_e32 v100, v223, v100
	v_mul_f32_e32 v101, v223, v101
	v_mul_f32_e32 v102, v223, v102
	v_mul_f32_e32 v103, v223, v103
	v_mul_f32_e32 v88, v225, v88
	v_mul_f32_e32 v89, v225, v89
	v_mul_f32_e32 v90, v225, v90
	v_mul_f32_e32 v91, v225, v91
	v_mul_f32_e32 v92, v225, v92
	v_mul_f32_e32 v93, v225, v93
	v_mul_f32_e32 v94, v225, v94
	v_mul_f32_e32 v95, v225, v95
	v_mul_f32_e32 v80, v225, v80
	v_mul_f32_e32 v81, v225, v81
	v_mul_f32_e32 v82, v225, v82
	v_mul_f32_e32 v83, v225, v83
	v_mul_f32_e32 v84, v225, v84
	v_mul_f32_e32 v85, v225, v85
	v_mul_f32_e32 v86, v225, v86
	v_mul_f32_e32 v87, v225, v87
	v_mul_f32_e32 v72, v227, v72
	v_mul_f32_e32 v73, v227, v73
	v_mul_f32_e32 v74, v227, v74
	v_mul_f32_e32 v75, v227, v75
	v_mul_f32_e32 v76, v227, v76
	v_mul_f32_e32 v77, v227, v77
	v_mul_f32_e32 v78, v227, v78
	v_mul_f32_e32 v79, v227, v79
	v_mul_f32_e32 v64, v227, v64
	v_mul_f32_e32 v65, v227, v65
	v_mul_f32_e32 v66, v227, v66
	v_mul_f32_e32 v67, v227, v67
	v_mul_f32_e32 v68, v227, v68
	v_mul_f32_e32 v69, v227, v69
	v_mul_f32_e32 v70, v227, v70
	v_mul_f32_e32 v71, v227, v71
	v_mul_f32_e32 v56, v229, v56
	v_mul_f32_e32 v57, v229, v57
	v_mul_f32_e32 v58, v229, v58
	v_mul_f32_e32 v59, v229, v59
	v_mul_f32_e32 v60, v229, v60
	v_mul_f32_e32 v61, v229, v61
	v_mul_f32_e32 v62, v229, v62
	v_mul_f32_e32 v63, v229, v63
	v_mul_f32_e32 v48, v229, v48
	v_mul_f32_e32 v49, v229, v49
	v_mul_f32_e32 v50, v229, v50
	v_mul_f32_e32 v51, v229, v51
	v_mul_f32_e32 v52, v229, v52
	v_mul_f32_e32 v53, v229, v53
	v_mul_f32_e32 v54, v229, v54
	v_mul_f32_e32 v55, v229, v55
	v_mul_f32_e32 v40, v231, v40
	v_mul_f32_e32 v41, v231, v41
	v_mul_f32_e32 v42, v231, v42
	v_mul_f32_e32 v43, v231, v43
	v_mul_f32_e32 v44, v231, v44
	v_mul_f32_e32 v45, v231, v45
	v_mul_f32_e32 v46, v231, v46
	v_mul_f32_e32 v47, v231, v47
	v_mul_f32_e32 v32, v231, v32
	v_mul_f32_e32 v33, v231, v33
	v_mul_f32_e32 v34, v231, v34
	v_mul_f32_e32 v35, v231, v35
	v_mul_f32_e32 v36, v231, v36
	v_mul_f32_e32 v37, v231, v37
	v_mul_f32_e32 v38, v231, v38
	v_mul_f32_e32 v39, v231, v39
	v_mul_f32_e32 v24, v233, v24
	v_mul_f32_e32 v25, v233, v25
	v_mul_f32_e32 v26, v233, v26
	v_mul_f32_e32 v27, v233, v27
	v_mul_f32_e32 v28, v233, v28
	v_mul_f32_e32 v29, v233, v29
	v_mul_f32_e32 v30, v233, v30
	v_mul_f32_e32 v31, v233, v31
	v_mul_f32_e32 v16, v233, v16
	v_mul_f32_e32 v17, v233, v17
	v_mul_f32_e32 v18, v233, v18
	v_mul_f32_e32 v19, v233, v19
	v_mul_f32_e32 v20, v233, v20
	v_mul_f32_e32 v21, v233, v21
	v_mul_f32_e32 v22, v233, v22
	v_mul_f32_e32 v23, v233, v23
	v_mul_f32_e32 v8, v235, v8
	v_mul_f32_e32 v9, v235, v9
	v_mul_f32_e32 v10, v235, v10
	v_mul_f32_e32 v11, v235, v11
	v_mul_f32_e32 v12, v235, v12
	v_mul_f32_e32 v13, v235, v13
	v_mul_f32_e32 v14, v235, v14
	v_mul_f32_e32 v15, v235, v15
	v_mul_f32_e32 v0, v235, v0
	v_mul_f32_e32 v1, v235, v1
	v_mul_f32_e32 v2, v235, v2
	v_mul_f32_e32 v3, v235, v3
	v_mul_f32_e32 v4, v235, v4
	v_mul_f32_e32 v5, v235, v5
	v_mul_f32_e32 v6, v235, v6
	v_mul_f32_e32 v7, v235, v7
	s_barrier
;     ...
;       if (EPI == 1) {
; #pragma unroll
;         for (int r = 0; r < 4; ++r) {
;           const int row = m0 + wm * 64 + mf * 16 + 4 * g + r;
; #pragma unroll
;           for (int nf = 0; nf < 4; ++nf) {
;             const int col = n0 + wn * 64 + nf * 16 + l15;
;             rvv[r][nf] = resid ? resid[(size_t)row * 1024 + col] : xrow(p, row)[col];
;           }
;         }
;       }
; #pragma unroll
;       for (int r = 0; r < 4; ++r) {
;         const int row = m0 + wm * 64 + mf * 16 + 4 * g + r;
;         if (EPI == 0) {
;           u16* proj = (u16*)(p.ws + OFF_PROJ) + (size_t)row * PROJ_LD;
;           if (n0 < 2048) {
;             const float2* rope = (const float2*)(p.ws + OFF_ROPE);
;             const int pi = row < NPROMPT ? (row & 2047) : 2048 + ((row - NPROMPT) & 7);
; #pragma unroll
;             for (int np = 0; np < 2; ++np) {
;               const int pc = n0 + wn * 64 + np * 32;
;               const int i = ((pc & 255) >> 5) * 16 + l15;
;               const float2 cs = rope[pi * 128 + i];
;               const float x1 = acc[mf][2 * np][r], x2 = acc[mf][2 * np + 1][r];
;               float y1 = x1 * cs.x - x2 * cs.y, y2 = x1 * cs.y + x2 * cs.x;
;               if (pc >= 1024) { y1 *= 0.0625f; y2 *= 0.0625f; }
;               const int f1 = (pc & ~255) + i;
;               proj[f1] = f2bf(y1);
;               proj[f1 + 128] = f2bf(y2);
;             }
;           } else {
; #pragma unroll
;             for (int nf = 0; nf < 4; ++nf) proj[n0 + wn * 64 + nf * 16 + l15] = f2bf(acc[mf][nf][r]);
;           }
;         } else if (EPI == 1) {
; #pragma unroll
;           for (int nf = 0; nf < 4; ++nf) {
;             const int col = n0 + wn * 64 + nf * 16 + l15;
;             const float a = (NH > 0) ? accT[mf][nf][r] : acc[mf][nf][r];
;             outf[(size_t)row * 1024 + col] = rvv[r][nf] + a;
;           }
	v_readlane_b32 s4, v255, 51
	v_readlane_b32 s1, v255, 52
	v_readlane_b32 s5, v255, 6
	v_and_b32_e32 v176, 15, v195
	v_lshrrev_b32_e32 v177, 4, v195
	s_lshr_b32 s6, s5, 2
	s_and_b32 s7, s5, 3
	s_lshl_b32 s6, s6, 6
	v_add_u32_e32 v178, s6, v176
	v_mul_u32_u24_e32 v178, 0x410, v178
	s_lshl_b32 s7, s7, 7
	v_lshl_add_u32 v178, v177, 4, v178
	v_add_u32_e32 v178, s7, v178
	s_lshl_b32 s7, s5, 4
	v_lshlrev_b32_e32 v179, 4, v195
	s_mul_i32 s6, s7, 0x410
	v_add_u32_e32 v180, s6, v179
	s_lshl_b32 s26, s4, 8
	s_add_i32 s26, s26, s7
	s_lshl_b32 s4, s26, 12
	s_lshl_b32 s27, s1, 10
	s_add_i32 s4, s4, s27
	v_add_u32_e32 v181, s4, v179
	s_add_u32 s20, s84, 0x15aa2000
	s_addc_u32 s21, s85, 0
	v_readlane_b32 s0, v255, 0
	v_readlane_b32 s1, v255, 1
	s_load_dwordx4 s[28:31], s[0:1], 0x90
	s_waitcnt lgkmcnt(0)
	s_mov_b32 s24, s30
	s_mov_b32 s25, s31
	s_add_u32 s22, s84, 0x26aa2000
	s_addc_u32 s23, s85, 0
	v_lshlrev_b32_e32 v174, 2, v195
	v_lshrrev_b32_e32 v175, 4, v195
	v_lshlrev_b32_e32 v175, 2, v175
	s_lshl_b32 s27, s26, 6
	v_readlane_b32 s1, v255, 52
	s_nop 3
	s_lshl_b32 s1, s1, 4
	s_add_i32 s1, s1, s27
	v_add_u32_e32 v175, s1, v175
	v_add_u32_e32 v174, s27, v174
	v_add_u32_e32 v138, 0x2000, v175
	v_add_u32_e32 v139, 0x2000, v174
	s_mov_b32 s2, 0x00010001
	s_mov_b32 s3, 0x00010001
	v_mov_b32_e32 v182, v181
	global_load_dwordx4 v[184:187], v182, s[20:21]
	v_add_u32_e32 v182, 0x1000, v182
	global_load_dwordx4 v[188:191], v182, s[20:21]
	v_add_u32_e32 v182, 0x1000, v182
	global_load_dwordx4 v[196:199], v182, s[20:21]
	v_add_u32_e32 v182, 0x1000, v182
	global_load_dwordx4 v[200:203], v182, s[20:21]
	v_add_u32_e32 v182, 0x1000, v182
	global_load_dwordx4 v[204:207], v182, s[20:21]
	v_add_u32_e32 v182, 0x1000, v182
	global_load_dwordx4 v[208:211], v182, s[20:21]
	v_add_u32_e32 v182, 0x1000, v182
	global_load_dwordx4 v[212:215], v182, s[20:21]
	v_add_u32_e32 v182, 0x1000, v182
	global_load_dwordx4 v[216:219], v182, s[20:21]
	v_add_u32_e32 v182, 0x1000, v182
	global_load_dwordx4 v[220:223], v182, s[20:21]
	v_add_u32_e32 v182, 0x1000, v182
	global_load_dwordx4 v[224:227], v182, s[20:21]
	v_add_u32_e32 v182, 0x1000, v182
	global_load_dwordx4 v[228:231], v182, s[20:21]
	v_add_u32_e32 v182, 0x1000, v182
	global_load_dwordx4 v[232:235], v182, s[20:21]
	v_add_u32_e32 v182, 0x1000, v182
	global_load_dwordx4 v[236:239], v182, s[20:21]
	v_add_u32_e32 v182, 0x1000, v182
	global_load_dwordx4 v[240:243], v182, s[20:21]
	v_add_u32_e32 v182, 0x1000, v182
	global_load_dwordx4 v[244:247], v182, s[20:21]
	v_add_u32_e32 v182, 0x1000, v182
	global_load_dwordx4 v[248:251], v182, s[20:21]
	ds_write_b128 v178, v[120:123]
	ds_write_b128 v178, v[124:127] offset:64
	ds_write_b128 v178, v[104:107] offset:16640
	ds_write_b128 v178, v[108:111] offset:16704
	ds_write_b128 v178, v[88:91] offset:33280
	ds_write_b128 v178, v[92:95] offset:33344
	ds_write_b128 v178, v[72:75] offset:49920
	ds_write_b128 v178, v[76:79] offset:49984
	ds_write_b128 v178, v[112:115] offset:512
	ds_write_b128 v178, v[116:119] offset:576
	ds_write_b128 v178, v[96:99] offset:17152
	ds_write_b128 v178, v[100:103] offset:17216
	ds_write_b128 v178, v[80:83] offset:33792
	ds_write_b128 v178, v[84:87] offset:33856
	ds_write_b128 v178, v[64:67] offset:50432
	ds_write_b128 v178, v[68:71] offset:50496
	s_waitcnt lgkmcnt(0)
	s_barrier
	ds_read_b128 v[64:67], v180
	ds_read_b128 v[68:71], v180 offset:1040
	ds_read_b128 v[72:75], v180 offset:2080
	ds_read_b128 v[76:79], v180 offset:3120
	ds_read_b128 v[80:83], v180 offset:4160
	ds_read_b128 v[84:87], v180 offset:5200
	ds_read_b128 v[88:91], v180 offset:6240
	ds_read_b128 v[92:95], v180 offset:7280
	ds_read_b128 v[96:99], v180 offset:8320
	ds_read_b128 v[100:103], v180 offset:9360
	ds_read_b128 v[104:107], v180 offset:10400
	ds_read_b128 v[108:111], v180 offset:11440
	ds_read_b128 v[112:115], v180 offset:12480
	ds_read_b128 v[116:119], v180 offset:13520
	ds_read_b128 v[120:123], v180 offset:14560
	ds_read_b128 v[124:127], v180 offset:15600
	s_waitcnt lgkmcnt(0)
	s_barrier
	v_mov_b32_e32 v182, v181
	s_waitcnt vmcnt(15)
	v_add_f32_e32 v64, v64, v184
	v_add_f32_e32 v65, v65, v185
	v_add_f32_e32 v66, v66, v186
	v_add_f32_e32 v67, v67, v187
	v_add_u32_e32 v182, 0x1000, v182
	s_waitcnt vmcnt(14)
	v_add_f32_e32 v68, v68, v188
	v_add_f32_e32 v69, v69, v189
	v_add_f32_e32 v70, v70, v190
	v_add_f32_e32 v71, v71, v191
	v_add_u32_e32 v182, 0x1000, v182
	s_waitcnt vmcnt(13)
	v_add_f32_e32 v72, v72, v196
	v_add_f32_e32 v73, v73, v197
	v_add_f32_e32 v74, v74, v198
	v_add_f32_e32 v75, v75, v199
	v_add_u32_e32 v182, 0x1000, v182
	s_waitcnt vmcnt(12)
	v_add_f32_e32 v76, v76, v200
	v_add_f32_e32 v77, v77, v201
	v_add_f32_e32 v78, v78, v202
	v_add_f32_e32 v79, v79, v203
	v_add_u32_e32 v182, 0x1000, v182
	s_waitcnt vmcnt(11)
	v_add_f32_e32 v80, v80, v204
	v_add_f32_e32 v81, v81, v205
	v_add_f32_e32 v82, v82, v206
	v_add_f32_e32 v83, v83, v207
	v_add_u32_e32 v182, 0x1000, v182
	s_waitcnt vmcnt(10)
	v_add_f32_e32 v84, v84, v208
	v_add_f32_e32 v85, v85, v209
	v_add_f32_e32 v86, v86, v210
	v_add_f32_e32 v87, v87, v211
	v_add_u32_e32 v182, 0x1000, v182
	s_waitcnt vmcnt(9)
	v_add_f32_e32 v88, v88, v212
	v_add_f32_e32 v89, v89, v213
	v_add_f32_e32 v90, v90, v214
	v_add_f32_e32 v91, v91, v215
	v_add_u32_e32 v182, 0x1000, v182
	s_waitcnt vmcnt(8)
	v_add_f32_e32 v92, v92, v216
	v_add_f32_e32 v93, v93, v217
	v_add_f32_e32 v94, v94, v218
	v_add_f32_e32 v95, v95, v219
	v_add_u32_e32 v182, 0x1000, v182
	s_waitcnt vmcnt(7)
	v_add_f32_e32 v96, v96, v220
	v_add_f32_e32 v97, v97, v221
	v_add_f32_e32 v98, v98, v222
	v_add_f32_e32 v99, v99, v223
	v_add_u32_e32 v182, 0x1000, v182
	s_waitcnt vmcnt(6)
; template <int MODE>
; __device__ void phase_norm(const Params& p, const float* __restrict__ X, const float* __restrict__ gain, const int rep) {
;     ...
;     float4 v[4];
;     float ss = 0.f;
; #pragma unroll
;     for (int i = 0; i < 4; ++i) {
;       v[i] = *(const float4*)(xr + i * 256 + lane * 4);
;       ss += v[i].x * v[i].x + v[i].y * v[i].y + v[i].z * v[i].z + v[i].w * v[i].w;
;     }
;     ss = wave_sum(ss);
;     ...
;         } else if (EPI == 1) {
; #pragma unroll
;           for (int nf = 0; nf < 4; ++nf) {
;             const int col = n0 + wn * 64 + nf * 16 + l15;
;             const float a = (NH > 0) ? accT[mf][nf][r] : acc[mf][nf][r];
;             outf[(size_t)row * 1024 + col] = rvv[r][nf] + a;
;           }
	v_add_f32_e32 v100, v100, v224
	v_add_f32_e32 v101, v101, v225
	v_add_f32_e32 v102, v102, v226
	v_add_f32_e32 v103, v103, v227
	v_add_u32_e32 v182, 0x1000, v182
	s_waitcnt vmcnt(5)
	v_add_f32_e32 v104, v104, v228
	v_add_f32_e32 v105, v105, v229
	v_add_f32_e32 v106, v106, v230
	v_add_f32_e32 v107, v107, v231
	v_add_u32_e32 v182, 0x1000, v182
	s_waitcnt vmcnt(4)
	v_add_f32_e32 v108, v108, v232
	v_add_f32_e32 v109, v109, v233
	v_add_f32_e32 v110, v110, v234
	v_add_f32_e32 v111, v111, v235
	v_add_u32_e32 v182, 0x1000, v182
	s_waitcnt vmcnt(3)
	v_add_f32_e32 v112, v112, v236
	v_add_f32_e32 v113, v113, v237
	v_add_f32_e32 v114, v114, v238
	v_add_f32_e32 v115, v115, v239
	v_add_u32_e32 v182, 0x1000, v182
	s_waitcnt vmcnt(2)
	v_add_f32_e32 v116, v116, v240
	v_add_f32_e32 v117, v117, v241
	v_add_f32_e32 v118, v118, v242
	v_add_f32_e32 v119, v119, v243
	v_add_u32_e32 v182, 0x1000, v182
	s_waitcnt vmcnt(1)
	v_add_f32_e32 v120, v120, v244
	v_add_f32_e32 v121, v121, v245
	v_add_f32_e32 v122, v122, v246
	v_add_f32_e32 v123, v123, v247
	v_add_u32_e32 v182, 0x1000, v182
	s_waitcnt vmcnt(0)
	v_add_f32_e32 v124, v124, v248
	v_add_f32_e32 v125, v125, v249
	v_add_f32_e32 v126, v126, v250
	v_add_f32_e32 v127, v127, v251
	v_mul_f32_e32 v134, v64, v64
	v_mul_f32_e32 v135, v68, v68
	v_mul_f32_e32 v136, v72, v72
	v_mul_f32_e32 v137, v76, v76
	v_fmac_f32_e32 v134, v65, v65
	v_fmac_f32_e32 v135, v69, v69
	v_fmac_f32_e32 v136, v73, v73
	v_fmac_f32_e32 v137, v77, v77
	v_fmac_f32_e32 v134, v66, v66
	v_fmac_f32_e32 v135, v70, v70
	v_fmac_f32_e32 v136, v74, v74
	v_fmac_f32_e32 v137, v78, v78
	v_fmac_f32_e32 v134, v67, v67
	v_fmac_f32_e32 v135, v71, v71
	v_fmac_f32_e32 v136, v75, v75
	v_fmac_f32_e32 v137, v79, v79
	v_add_f32_dpp v134, v134, v134 quad_perm:[1,0,3,2] row_mask:0xf bank_mask:0xf bound_ctrl:1
	v_add_f32_dpp v135, v135, v135 quad_perm:[1,0,3,2] row_mask:0xf bank_mask:0xf bound_ctrl:1
	v_add_f32_dpp v136, v136, v136 quad_perm:[1,0,3,2] row_mask:0xf bank_mask:0xf bound_ctrl:1
	v_add_f32_dpp v137, v137, v137 quad_perm:[1,0,3,2] row_mask:0xf bank_mask:0xf bound_ctrl:1
	v_add_f32_dpp v134, v134, v134 quad_perm:[2,3,0,1] row_mask:0xf bank_mask:0xf bound_ctrl:1
	v_add_f32_dpp v135, v135, v135 quad_perm:[2,3,0,1] row_mask:0xf bank_mask:0xf bound_ctrl:1
	v_add_f32_dpp v136, v136, v136 quad_perm:[2,3,0,1] row_mask:0xf bank_mask:0xf bound_ctrl:1
	v_add_f32_dpp v137, v137, v137 quad_perm:[2,3,0,1] row_mask:0xf bank_mask:0xf bound_ctrl:1
	v_add_f32_dpp v134, v134, v134 row_ror:4 row_mask:0xf bank_mask:0xf bound_ctrl:1
	v_add_f32_dpp v135, v135, v135 row_ror:4 row_mask:0xf bank_mask:0xf bound_ctrl:1
	v_add_f32_dpp v136, v136, v136 row_ror:4 row_mask:0xf bank_mask:0xf bound_ctrl:1
	v_add_f32_dpp v137, v137, v137 row_ror:4 row_mask:0xf bank_mask:0xf bound_ctrl:1
	v_add_f32_dpp v134, v134, v134 row_ror:8 row_mask:0xf bank_mask:0xf bound_ctrl:1
	v_add_f32_dpp v135, v135, v135 row_ror:8 row_mask:0xf bank_mask:0xf bound_ctrl:1
	v_add_f32_dpp v136, v136, v136 row_ror:8 row_mask:0xf bank_mask:0xf bound_ctrl:1
	v_add_f32_dpp v137, v137, v137 row_ror:8 row_mask:0xf bank_mask:0xf bound_ctrl:1
	s_mov_b64 s[34:35], exec
	s_mov_b64 exec, s[2:3]
	global_store_dword v175, v134, s[22:23] sc0 sc1
	global_store_dword v175, v135, s[22:23] offset:64 sc0 sc1
	global_store_dword v175, v136, s[22:23] offset:128 sc0 sc1
	global_store_dword v175, v137, s[22:23] offset:192 sc0 sc1
	s_mov_b64 exec, s[34:35]
	s_nop 1
	v_mul_f32_e32 v134, v80, v80
	v_mul_f32_e32 v135, v84, v84
	v_mul_f32_e32 v136, v88, v88
	v_mul_f32_e32 v137, v92, v92
	v_fmac_f32_e32 v134, v81, v81
	v_fmac_f32_e32 v135, v85, v85
	v_fmac_f32_e32 v136, v89, v89
	v_fmac_f32_e32 v137, v93, v93
	v_fmac_f32_e32 v134, v82, v82
	v_fmac_f32_e32 v135, v86, v86
	v_fmac_f32_e32 v136, v90, v90
	v_fmac_f32_e32 v137, v94, v94
	v_fmac_f32_e32 v134, v83, v83
	v_fmac_f32_e32 v135, v87, v87
	v_fmac_f32_e32 v136, v91, v91
	v_fmac_f32_e32 v137, v95, v95
	v_add_f32_dpp v134, v134, v134 quad_perm:[1,0,3,2] row_mask:0xf bank_mask:0xf bound_ctrl:1
	v_add_f32_dpp v135, v135, v135 quad_perm:[1,0,3,2] row_mask:0xf bank_mask:0xf bound_ctrl:1
	v_add_f32_dpp v136, v136, v136 quad_perm:[1,0,3,2] row_mask:0xf bank_mask:0xf bound_ctrl:1
	v_add_f32_dpp v137, v137, v137 quad_perm:[1,0,3,2] row_mask:0xf bank_mask:0xf bound_ctrl:1
	v_add_f32_dpp v134, v134, v134 quad_perm:[2,3,0,1] row_mask:0xf bank_mask:0xf bound_ctrl:1
	v_add_f32_dpp v135, v135, v135 quad_perm:[2,3,0,1] row_mask:0xf bank_mask:0xf bound_ctrl:1
	v_add_f32_dpp v136, v136, v136 quad_perm:[2,3,0,1] row_mask:0xf bank_mask:0xf bound_ctrl:1
	v_add_f32_dpp v137, v137, v137 quad_perm:[2,3,0,1] row_mask:0xf bank_mask:0xf bound_ctrl:1
	v_add_f32_dpp v134, v134, v134 row_ror:4 row_mask:0xf bank_mask:0xf bound_ctrl:1
	v_add_f32_dpp v135, v135, v135 row_ror:4 row_mask:0xf bank_mask:0xf bound_ctrl:1
	v_add_f32_dpp v136, v136, v136 row_ror:4 row_mask:0xf bank_mask:0xf bound_ctrl:1
	v_add_f32_dpp v137, v137, v137 row_ror:4 row_mask:0xf bank_mask:0xf bound_ctrl:1
	v_add_f32_dpp v134, v134, v134 row_ror:8 row_mask:0xf bank_mask:0xf bound_ctrl:1
	v_add_f32_dpp v135, v135, v135 row_ror:8 row_mask:0xf bank_mask:0xf bound_ctrl:1
	v_add_f32_dpp v136, v136, v136 row_ror:8 row_mask:0xf bank_mask:0xf bound_ctrl:1
	v_add_f32_dpp v137, v137, v137 row_ror:8 row_mask:0xf bank_mask:0xf bound_ctrl:1
	s_mov_b64 s[34:35], exec
	s_mov_b64 exec, s[2:3]
	global_store_dword v175, v134, s[22:23] offset:256 sc0 sc1
	global_store_dword v175, v135, s[22:23] offset:320 sc0 sc1
	global_store_dword v175, v136, s[22:23] offset:384 sc0 sc1
	global_store_dword v175, v137, s[22:23] offset:448 sc0 sc1
	s_mov_b64 exec, s[34:35]
	s_nop 1
; template <int MODE>
; __device__ void phase_norm(const Params& p, const float* __restrict__ X, const float* __restrict__ gain, const int rep) {
;     ...
;     float4 v[4];
;     float ss = 0.f;
; #pragma unroll
;     for (int i = 0; i < 4; ++i) {
;       v[i] = *(const float4*)(xr + i * 256 + lane * 4);
;       ss += v[i].x * v[i].x + v[i].y * v[i].y + v[i].z * v[i].z + v[i].w * v[i].w;
;     }
;     ss = wave_sum(ss);
;     ...
;       if (EPI == 1) {
; #pragma unroll
;         for (int r = 0; r < 4; ++r) {
;           const int row = m0 + wm * 64 + mf * 16 + 4 * g + r;
; #pragma unroll
;           for (int nf = 0; nf < 4; ++nf) {
;             const int col = n0 + wn * 64 + nf * 16 + l15;
;             rvv[r][nf] = resid ? resid[(size_t)row * 1024 + col] : xrow(p, row)[col];
;           }
;         }
;       }
	v_mul_f32_e32 v134, v96, v96
	v_mul_f32_e32 v135, v100, v100
	v_mul_f32_e32 v136, v104, v104
	v_mul_f32_e32 v137, v108, v108
	v_fmac_f32_e32 v134, v97, v97
	v_fmac_f32_e32 v135, v101, v101
	v_fmac_f32_e32 v136, v105, v105
	v_fmac_f32_e32 v137, v109, v109
	v_fmac_f32_e32 v134, v98, v98
	v_fmac_f32_e32 v135, v102, v102
	v_fmac_f32_e32 v136, v106, v106
	v_fmac_f32_e32 v137, v110, v110
	v_fmac_f32_e32 v134, v99, v99
	v_fmac_f32_e32 v135, v103, v103
	v_fmac_f32_e32 v136, v107, v107
	v_fmac_f32_e32 v137, v111, v111
	v_add_f32_dpp v134, v134, v134 quad_perm:[1,0,3,2] row_mask:0xf bank_mask:0xf bound_ctrl:1
	v_add_f32_dpp v135, v135, v135 quad_perm:[1,0,3,2] row_mask:0xf bank_mask:0xf bound_ctrl:1
	v_add_f32_dpp v136, v136, v136 quad_perm:[1,0,3,2] row_mask:0xf bank_mask:0xf bound_ctrl:1
	v_add_f32_dpp v137, v137, v137 quad_perm:[1,0,3,2] row_mask:0xf bank_mask:0xf bound_ctrl:1
	v_add_f32_dpp v134, v134, v134 quad_perm:[2,3,0,1] row_mask:0xf bank_mask:0xf bound_ctrl:1
	v_add_f32_dpp v135, v135, v135 quad_perm:[2,3,0,1] row_mask:0xf bank_mask:0xf bound_ctrl:1
	v_add_f32_dpp v136, v136, v136 quad_perm:[2,3,0,1] row_mask:0xf bank_mask:0xf bound_ctrl:1
	v_add_f32_dpp v137, v137, v137 quad_perm:[2,3,0,1] row_mask:0xf bank_mask:0xf bound_ctrl:1
	v_add_f32_dpp v134, v134, v134 row_ror:4 row_mask:0xf bank_mask:0xf bound_ctrl:1
	v_add_f32_dpp v135, v135, v135 row_ror:4 row_mask:0xf bank_mask:0xf bound_ctrl:1
	v_add_f32_dpp v136, v136, v136 row_ror:4 row_mask:0xf bank_mask:0xf bound_ctrl:1
	v_add_f32_dpp v137, v137, v137 row_ror:4 row_mask:0xf bank_mask:0xf bound_ctrl:1
	v_add_f32_dpp v134, v134, v134 row_ror:8 row_mask:0xf bank_mask:0xf bound_ctrl:1
	v_add_f32_dpp v135, v135, v135 row_ror:8 row_mask:0xf bank_mask:0xf bound_ctrl:1
	v_add_f32_dpp v136, v136, v136 row_ror:8 row_mask:0xf bank_mask:0xf bound_ctrl:1
	v_add_f32_dpp v137, v137, v137 row_ror:8 row_mask:0xf bank_mask:0xf bound_ctrl:1
	s_mov_b64 s[34:35], exec
	s_mov_b64 exec, s[2:3]
	global_store_dword v175, v134, s[22:23] offset:512 sc0 sc1
	global_store_dword v175, v135, s[22:23] offset:576 sc0 sc1
	global_store_dword v175, v136, s[22:23] offset:640 sc0 sc1
	global_store_dword v175, v137, s[22:23] offset:704 sc0 sc1
	s_mov_b64 exec, s[34:35]
	s_nop 1
	v_mul_f32_e32 v134, v112, v112
	v_mul_f32_e32 v135, v116, v116
	v_mul_f32_e32 v136, v120, v120
	v_mul_f32_e32 v137, v124, v124
	v_fmac_f32_e32 v134, v113, v113
	v_fmac_f32_e32 v135, v117, v117
	v_fmac_f32_e32 v136, v121, v121
	v_fmac_f32_e32 v137, v125, v125
	v_fmac_f32_e32 v134, v114, v114
	v_fmac_f32_e32 v135, v118, v118
	v_fmac_f32_e32 v136, v122, v122
	v_fmac_f32_e32 v137, v126, v126
	v_fmac_f32_e32 v134, v115, v115
	v_fmac_f32_e32 v135, v119, v119
	v_fmac_f32_e32 v136, v123, v123
	v_fmac_f32_e32 v137, v127, v127
	v_add_f32_dpp v134, v134, v134 quad_perm:[1,0,3,2] row_mask:0xf bank_mask:0xf bound_ctrl:1
	v_add_f32_dpp v135, v135, v135 quad_perm:[1,0,3,2] row_mask:0xf bank_mask:0xf bound_ctrl:1
	v_add_f32_dpp v136, v136, v136 quad_perm:[1,0,3,2] row_mask:0xf bank_mask:0xf bound_ctrl:1
	v_add_f32_dpp v137, v137, v137 quad_perm:[1,0,3,2] row_mask:0xf bank_mask:0xf bound_ctrl:1
	v_add_f32_dpp v134, v134, v134 quad_perm:[2,3,0,1] row_mask:0xf bank_mask:0xf bound_ctrl:1
	v_add_f32_dpp v135, v135, v135 quad_perm:[2,3,0,1] row_mask:0xf bank_mask:0xf bound_ctrl:1
	v_add_f32_dpp v136, v136, v136 quad_perm:[2,3,0,1] row_mask:0xf bank_mask:0xf bound_ctrl:1
	v_add_f32_dpp v137, v137, v137 quad_perm:[2,3,0,1] row_mask:0xf bank_mask:0xf bound_ctrl:1
	v_add_f32_dpp v134, v134, v134 row_ror:4 row_mask:0xf bank_mask:0xf bound_ctrl:1
	v_add_f32_dpp v135, v135, v135 row_ror:4 row_mask:0xf bank_mask:0xf bound_ctrl:1
	v_add_f32_dpp v136, v136, v136 row_ror:4 row_mask:0xf bank_mask:0xf bound_ctrl:1
	v_add_f32_dpp v137, v137, v137 row_ror:4 row_mask:0xf bank_mask:0xf bound_ctrl:1
	v_add_f32_dpp v134, v134, v134 row_ror:8 row_mask:0xf bank_mask:0xf bound_ctrl:1
	v_add_f32_dpp v135, v135, v135 row_ror:8 row_mask:0xf bank_mask:0xf bound_ctrl:1
	v_add_f32_dpp v136, v136, v136 row_ror:8 row_mask:0xf bank_mask:0xf bound_ctrl:1
	v_add_f32_dpp v137, v137, v137 row_ror:8 row_mask:0xf bank_mask:0xf bound_ctrl:1
	s_mov_b64 s[34:35], exec
	s_mov_b64 exec, s[2:3]
	global_store_dword v175, v134, s[22:23] offset:768 sc0 sc1
	global_store_dword v175, v135, s[22:23] offset:832 sc0 sc1
	global_store_dword v175, v136, s[22:23] offset:896 sc0 sc1
	global_store_dword v175, v137, s[22:23] offset:960 sc0 sc1
	s_mov_b64 exec, s[34:35]
	s_nop 1
	v_add_u32_e32 v181, 0x80000, v181
	v_mov_b32_e32 v182, v181
	global_load_dwordx4 v[184:187], v182, s[20:21]
	v_add_u32_e32 v182, 0x1000, v182
	global_load_dwordx4 v[188:191], v182, s[20:21]
	v_add_u32_e32 v182, 0x1000, v182
	global_load_dwordx4 v[196:199], v182, s[20:21]
	v_add_u32_e32 v182, 0x1000, v182
	global_load_dwordx4 v[200:203], v182, s[20:21]
	v_add_u32_e32 v182, 0x1000, v182
	global_load_dwordx4 v[204:207], v182, s[20:21]
	v_add_u32_e32 v182, 0x1000, v182
	global_load_dwordx4 v[208:211], v182, s[20:21]
	v_add_u32_e32 v182, 0x1000, v182
	global_load_dwordx4 v[212:215], v182, s[20:21]
	v_add_u32_e32 v182, 0x1000, v182
	global_load_dwordx4 v[216:219], v182, s[20:21]
	v_add_u32_e32 v182, 0x1000, v182
	global_load_dwordx4 v[220:223], v182, s[20:21]
	v_add_u32_e32 v182, 0x1000, v182
	global_load_dwordx4 v[224:227], v182, s[20:21]
	v_add_u32_e32 v182, 0x1000, v182
	global_load_dwordx4 v[228:231], v182, s[20:21]
	v_add_u32_e32 v182, 0x1000, v182
	global_load_dwordx4 v[232:235], v182, s[20:21]
	v_add_u32_e32 v182, 0x1000, v182
	global_load_dwordx4 v[236:239], v182, s[20:21]
	v_add_u32_e32 v182, 0x1000, v182
	global_load_dwordx4 v[240:243], v182, s[20:21]
	v_add_u32_e32 v182, 0x1000, v182
	global_load_dwordx4 v[244:247], v182, s[20:21]
	v_add_u32_e32 v182, 0x1000, v182
	global_load_dwordx4 v[248:251], v182, s[20:21]
	ds_write_b128 v178, v[56:59]
	ds_write_b128 v178, v[60:63] offset:64
	ds_write_b128 v178, v[40:43] offset:16640
	ds_write_b128 v178, v[44:47] offset:16704
	ds_write_b128 v178, v[24:27] offset:33280
	ds_write_b128 v178, v[28:31] offset:33344
	ds_write_b128 v178, v[8:11] offset:49920
	ds_write_b128 v178, v[12:15] offset:49984
	ds_write_b128 v178, v[48:51] offset:512
	ds_write_b128 v178, v[52:55] offset:576
	ds_write_b128 v178, v[32:35] offset:17152
	ds_write_b128 v178, v[36:39] offset:17216
	ds_write_b128 v178, v[16:19] offset:33792
	ds_write_b128 v178, v[20:23] offset:33856
	ds_write_b128 v178, v[0:3] offset:50432
	ds_write_b128 v178, v[4:7] offset:50496
	s_waitcnt lgkmcnt(0)
	s_barrier
; template <int MODE>
; __device__ void phase_norm(const Params& p, const float* __restrict__ X, const float* __restrict__ gain, const int rep) {
;     ...
;     float4 v[4];
;     float ss = 0.f;
; #pragma unroll
;     for (int i = 0; i < 4; ++i) {
;       v[i] = *(const float4*)(xr + i * 256 + lane * 4);
;       ss += v[i].x * v[i].x + v[i].y * v[i].y + v[i].z * v[i].z + v[i].w * v[i].w;
;     }
;     ss = wave_sum(ss);
;     ...
;         } else if (EPI == 1) {
; #pragma unroll
;           for (int nf = 0; nf < 4; ++nf) {
;             const int col = n0 + wn * 64 + nf * 16 + l15;
;             const float a = (NH > 0) ? accT[mf][nf][r] : acc[mf][nf][r];
;             outf[(size_t)row * 1024 + col] = rvv[r][nf] + a;
;           }
	ds_read_b128 v[0:3], v180
	ds_read_b128 v[4:7], v180 offset:1040
	ds_read_b128 v[8:11], v180 offset:2080
	ds_read_b128 v[12:15], v180 offset:3120
	ds_read_b128 v[16:19], v180 offset:4160
	ds_read_b128 v[20:23], v180 offset:5200
	ds_read_b128 v[24:27], v180 offset:6240
	ds_read_b128 v[28:31], v180 offset:7280
	ds_read_b128 v[32:35], v180 offset:8320
	ds_read_b128 v[36:39], v180 offset:9360
	ds_read_b128 v[40:43], v180 offset:10400
	ds_read_b128 v[44:47], v180 offset:11440
	ds_read_b128 v[48:51], v180 offset:12480
	ds_read_b128 v[52:55], v180 offset:13520
	ds_read_b128 v[56:59], v180 offset:14560
	ds_read_b128 v[60:63], v180 offset:15600
	s_waitcnt lgkmcnt(0)
	s_barrier
	v_mov_b32_e32 v182, v181
	s_waitcnt vmcnt(15)
	v_add_f32_e32 v0, v0, v184
	v_add_f32_e32 v1, v1, v185
	v_add_f32_e32 v2, v2, v186
	v_add_f32_e32 v3, v3, v187
	v_add_u32_e32 v182, 0x1000, v182
	s_waitcnt vmcnt(14)
	v_add_f32_e32 v4, v4, v188
	v_add_f32_e32 v5, v5, v189
	v_add_f32_e32 v6, v6, v190
	v_add_f32_e32 v7, v7, v191
	v_add_u32_e32 v182, 0x1000, v182
	s_waitcnt vmcnt(13)
	v_add_f32_e32 v8, v8, v196
	v_add_f32_e32 v9, v9, v197
	v_add_f32_e32 v10, v10, v198
	v_add_f32_e32 v11, v11, v199
	v_add_u32_e32 v182, 0x1000, v182
	s_waitcnt vmcnt(12)
	v_add_f32_e32 v12, v12, v200
	v_add_f32_e32 v13, v13, v201
	v_add_f32_e32 v14, v14, v202
	v_add_f32_e32 v15, v15, v203
	v_add_u32_e32 v182, 0x1000, v182
	s_waitcnt vmcnt(11)
	v_add_f32_e32 v16, v16, v204
	v_add_f32_e32 v17, v17, v205
	v_add_f32_e32 v18, v18, v206
	v_add_f32_e32 v19, v19, v207
	v_add_u32_e32 v182, 0x1000, v182
	s_waitcnt vmcnt(10)
	v_add_f32_e32 v20, v20, v208
	v_add_f32_e32 v21, v21, v209
	v_add_f32_e32 v22, v22, v210
	v_add_f32_e32 v23, v23, v211
	v_add_u32_e32 v182, 0x1000, v182
	s_waitcnt vmcnt(9)
	v_add_f32_e32 v24, v24, v212
	v_add_f32_e32 v25, v25, v213
	v_add_f32_e32 v26, v26, v214
	v_add_f32_e32 v27, v27, v215
	v_add_u32_e32 v182, 0x1000, v182
	s_waitcnt vmcnt(8)
	v_add_f32_e32 v28, v28, v216
	v_add_f32_e32 v29, v29, v217
	v_add_f32_e32 v30, v30, v218
	v_add_f32_e32 v31, v31, v219
	v_add_u32_e32 v182, 0x1000, v182
	s_waitcnt vmcnt(7)
	v_add_f32_e32 v32, v32, v220
	v_add_f32_e32 v33, v33, v221
	v_add_f32_e32 v34, v34, v222
	v_add_f32_e32 v35, v35, v223
	v_add_u32_e32 v182, 0x1000, v182
	s_waitcnt vmcnt(6)
	v_add_f32_e32 v36, v36, v224
	v_add_f32_e32 v37, v37, v225
	v_add_f32_e32 v38, v38, v226
	v_add_f32_e32 v39, v39, v227
	v_add_u32_e32 v182, 0x1000, v182
	s_waitcnt vmcnt(5)
	v_add_f32_e32 v40, v40, v228
	v_add_f32_e32 v41, v41, v229
	v_add_f32_e32 v42, v42, v230
	v_add_f32_e32 v43, v43, v231
	v_add_u32_e32 v182, 0x1000, v182
	s_waitcnt vmcnt(4)
	v_add_f32_e32 v44, v44, v232
	v_add_f32_e32 v45, v45, v233
	v_add_f32_e32 v46, v46, v234
	v_add_f32_e32 v47, v47, v235
	v_add_u32_e32 v182, 0x1000, v182
	s_waitcnt vmcnt(3)
	v_add_f32_e32 v48, v48, v236
	v_add_f32_e32 v49, v49, v237
	v_add_f32_e32 v50, v50, v238
	v_add_f32_e32 v51, v51, v239
	v_add_u32_e32 v182, 0x1000, v182
	s_waitcnt vmcnt(2)
	v_add_f32_e32 v52, v52, v240
	v_add_f32_e32 v53, v53, v241
	v_add_f32_e32 v54, v54, v242
	v_add_f32_e32 v55, v55, v243
	v_add_u32_e32 v182, 0x1000, v182
	s_waitcnt vmcnt(1)
	v_add_f32_e32 v56, v56, v244
	v_add_f32_e32 v57, v57, v245
	v_add_f32_e32 v58, v58, v246
	v_add_f32_e32 v59, v59, v247
	v_add_u32_e32 v182, 0x1000, v182
	s_waitcnt vmcnt(0)
	v_add_f32_e32 v60, v60, v248
	v_add_f32_e32 v61, v61, v249
	v_add_f32_e32 v62, v62, v250
	v_add_f32_e32 v63, v63, v251
	v_mul_f32_e32 v134, v0, v0
	v_mul_f32_e32 v135, v4, v4
	v_mul_f32_e32 v136, v8, v8
	v_mul_f32_e32 v137, v12, v12
	v_fmac_f32_e32 v134, v1, v1
	v_fmac_f32_e32 v135, v5, v5
	v_fmac_f32_e32 v136, v9, v9
	v_fmac_f32_e32 v137, v13, v13
	v_fmac_f32_e32 v134, v2, v2
	v_fmac_f32_e32 v135, v6, v6
	v_fmac_f32_e32 v136, v10, v10
	v_fmac_f32_e32 v137, v14, v14
	v_fmac_f32_e32 v134, v3, v3
	v_fmac_f32_e32 v135, v7, v7
	v_fmac_f32_e32 v136, v11, v11
	v_fmac_f32_e32 v137, v15, v15
	v_add_f32_dpp v134, v134, v134 quad_perm:[1,0,3,2] row_mask:0xf bank_mask:0xf bound_ctrl:1
	v_add_f32_dpp v135, v135, v135 quad_perm:[1,0,3,2] row_mask:0xf bank_mask:0xf bound_ctrl:1
	v_add_f32_dpp v136, v136, v136 quad_perm:[1,0,3,2] row_mask:0xf bank_mask:0xf bound_ctrl:1
	v_add_f32_dpp v137, v137, v137 quad_perm:[1,0,3,2] row_mask:0xf bank_mask:0xf bound_ctrl:1
	v_add_f32_dpp v134, v134, v134 quad_perm:[2,3,0,1] row_mask:0xf bank_mask:0xf bound_ctrl:1
	v_add_f32_dpp v135, v135, v135 quad_perm:[2,3,0,1] row_mask:0xf bank_mask:0xf bound_ctrl:1
	v_add_f32_dpp v136, v136, v136 quad_perm:[2,3,0,1] row_mask:0xf bank_mask:0xf bound_ctrl:1
	v_add_f32_dpp v137, v137, v137 quad_perm:[2,3,0,1] row_mask:0xf bank_mask:0xf bound_ctrl:1
	v_add_f32_dpp v134, v134, v134 row_ror:4 row_mask:0xf bank_mask:0xf bound_ctrl:1
	v_add_f32_dpp v135, v135, v135 row_ror:4 row_mask:0xf bank_mask:0xf bound_ctrl:1
	v_add_f32_dpp v136, v136, v136 row_ror:4 row_mask:0xf bank_mask:0xf bound_ctrl:1
	v_add_f32_dpp v137, v137, v137 row_ror:4 row_mask:0xf bank_mask:0xf bound_ctrl:1
	v_add_f32_dpp v134, v134, v134 row_ror:8 row_mask:0xf bank_mask:0xf bound_ctrl:1
	v_add_f32_dpp v135, v135, v135 row_ror:8 row_mask:0xf bank_mask:0xf bound_ctrl:1
	v_add_f32_dpp v136, v136, v136 row_ror:8 row_mask:0xf bank_mask:0xf bound_ctrl:1
	v_add_f32_dpp v137, v137, v137 row_ror:8 row_mask:0xf bank_mask:0xf bound_ctrl:1
	s_mov_b64 s[34:35], exec
	s_mov_b64 exec, s[2:3]
	global_store_dword v138, v134, s[22:23] sc0 sc1
	global_store_dword v138, v135, s[22:23] offset:64 sc0 sc1
	global_store_dword v138, v136, s[22:23] offset:128 sc0 sc1
	global_store_dword v138, v137, s[22:23] offset:192 sc0 sc1
	s_mov_b64 exec, s[34:35]
	s_nop 1
	v_mul_f32_e32 v134, v16, v16
; __device__ __forceinline__ unsigned xb_ld(unsigned* p) { return __hip_atomic_load(p, __ATOMIC_RELAXED, __HIP_MEMORY_SCOPE_AGENT); }
; __device__ __forceinline__ unsigned xb_add(unsigned* p, unsigned v) { return __hip_atomic_fetch_add(p, v, __ATOMIC_RELAXED, __HIP_MEMORY_SCOPE_AGENT); }
; #define XB_SPIN(cond, bar) do { unsigned _sp = 0; while (cond) { __builtin_amdgcn_s_sleep(1); \
;     if ((++_sp & 255u) == 0u) { if (xb_ld(&(bar)[XB_TMO])) break; if (_sp > XB_SPIN_CAP) { atomicAdd(&(bar)[XB_TMO], 1u); break; } } } } while (0)
; template <int MODE>
; __device__ void phase_norm(const Params& p, const float* __restrict__ X, const float* __restrict__ gain, const int rep) {
;     ...
;     float4 v[4];
;     float ss = 0.f;
; #pragma unroll
;     for (int i = 0; i < 4; ++i) {
;       v[i] = *(const float4*)(xr + i * 256 + lane * 4);
;       ss += v[i].x * v[i].x + v[i].y * v[i].y + v[i].z * v[i].z + v[i].w * v[i].w;
;     }
;     ss = wave_sum(ss);
; __device__ __forceinline__ void xcd_barrier(const XcdBarrier& b, const int wvs) {
;     ...
;     const unsigned old = xb_add(&bar[XB_XSUB(b.x)], 1u);
;     const unsigned gen = old / nloc;
;     if (old + 1u == (gen + 1u) * nloc) {
;       __builtin_amdgcn_fence(__ATOMIC_RELEASE, "agent");
;       asm volatile("s_waitcnt vmcnt(0)" ::: "memory");
;       const unsigned og = xb_add(&bar[XB_TOP], 1u);
;       const unsigned tg = og / nx;
;       if (og + 1u == (tg + 1u) * nx) xb_add(&bar[XB_TOPGEN], 1u);
;       else XB_SPIN(xb_ld(&bar[XB_TOPGEN]) == tg, bar);
;       __builtin_amdgcn_fence(__ATOMIC_ACQUIRE, "agent");
;       xb_add(&bar[XB_XGEN(b.x)], 1u);
;       asm volatile("s_waitcnt vmcnt(0)" ::: "memory");
;     } else {
;       XB_SPIN(xb_ld(&bar[XB_XGEN(b.x)]) == gen, bar);
	v_mul_f32_e32 v135, v20, v20
	v_mul_f32_e32 v136, v24, v24
	v_mul_f32_e32 v137, v28, v28
	v_fmac_f32_e32 v134, v17, v17
	v_fmac_f32_e32 v135, v21, v21
	v_fmac_f32_e32 v136, v25, v25
	v_fmac_f32_e32 v137, v29, v29
	v_fmac_f32_e32 v134, v18, v18
	v_fmac_f32_e32 v135, v22, v22
	v_fmac_f32_e32 v136, v26, v26
	v_fmac_f32_e32 v137, v30, v30
	v_fmac_f32_e32 v134, v19, v19
	v_fmac_f32_e32 v135, v23, v23
	v_fmac_f32_e32 v136, v27, v27
	v_fmac_f32_e32 v137, v31, v31
	v_add_f32_dpp v134, v134, v134 quad_perm:[1,0,3,2] row_mask:0xf bank_mask:0xf bound_ctrl:1
	v_add_f32_dpp v135, v135, v135 quad_perm:[1,0,3,2] row_mask:0xf bank_mask:0xf bound_ctrl:1
	v_add_f32_dpp v136, v136, v136 quad_perm:[1,0,3,2] row_mask:0xf bank_mask:0xf bound_ctrl:1
	v_add_f32_dpp v137, v137, v137 quad_perm:[1,0,3,2] row_mask:0xf bank_mask:0xf bound_ctrl:1
	v_add_f32_dpp v134, v134, v134 quad_perm:[2,3,0,1] row_mask:0xf bank_mask:0xf bound_ctrl:1
	v_add_f32_dpp v135, v135, v135 quad_perm:[2,3,0,1] row_mask:0xf bank_mask:0xf bound_ctrl:1
	v_add_f32_dpp v136, v136, v136 quad_perm:[2,3,0,1] row_mask:0xf bank_mask:0xf bound_ctrl:1
	v_add_f32_dpp v137, v137, v137 quad_perm:[2,3,0,1] row_mask:0xf bank_mask:0xf bound_ctrl:1
	v_add_f32_dpp v134, v134, v134 row_ror:4 row_mask:0xf bank_mask:0xf bound_ctrl:1
	v_add_f32_dpp v135, v135, v135 row_ror:4 row_mask:0xf bank_mask:0xf bound_ctrl:1
	v_add_f32_dpp v136, v136, v136 row_ror:4 row_mask:0xf bank_mask:0xf bound_ctrl:1
	v_add_f32_dpp v137, v137, v137 row_ror:4 row_mask:0xf bank_mask:0xf bound_ctrl:1
	v_add_f32_dpp v134, v134, v134 row_ror:8 row_mask:0xf bank_mask:0xf bound_ctrl:1
	v_add_f32_dpp v135, v135, v135 row_ror:8 row_mask:0xf bank_mask:0xf bound_ctrl:1
	v_add_f32_dpp v136, v136, v136 row_ror:8 row_mask:0xf bank_mask:0xf bound_ctrl:1
	v_add_f32_dpp v137, v137, v137 row_ror:8 row_mask:0xf bank_mask:0xf bound_ctrl:1
	s_mov_b64 s[34:35], exec
	s_mov_b64 exec, s[2:3]
	global_store_dword v138, v134, s[22:23] offset:256 sc0 sc1
	global_store_dword v138, v135, s[22:23] offset:320 sc0 sc1
	global_store_dword v138, v136, s[22:23] offset:384 sc0 sc1
	global_store_dword v138, v137, s[22:23] offset:448 sc0 sc1
	s_mov_b64 exec, s[34:35]
	s_nop 1
	v_mul_f32_e32 v134, v32, v32
	v_mul_f32_e32 v135, v36, v36
	v_mul_f32_e32 v136, v40, v40
	v_mul_f32_e32 v137, v44, v44
	v_fmac_f32_e32 v134, v33, v33
	v_fmac_f32_e32 v135, v37, v37
	v_fmac_f32_e32 v136, v41, v41
	v_fmac_f32_e32 v137, v45, v45
	v_fmac_f32_e32 v134, v34, v34
	v_fmac_f32_e32 v135, v38, v38
	v_fmac_f32_e32 v136, v42, v42
	v_fmac_f32_e32 v137, v46, v46
	v_fmac_f32_e32 v134, v35, v35
	v_fmac_f32_e32 v135, v39, v39
	v_fmac_f32_e32 v136, v43, v43
	v_fmac_f32_e32 v137, v47, v47
	v_add_f32_dpp v134, v134, v134 quad_perm:[1,0,3,2] row_mask:0xf bank_mask:0xf bound_ctrl:1
	v_add_f32_dpp v135, v135, v135 quad_perm:[1,0,3,2] row_mask:0xf bank_mask:0xf bound_ctrl:1
	v_add_f32_dpp v136, v136, v136 quad_perm:[1,0,3,2] row_mask:0xf bank_mask:0xf bound_ctrl:1
	v_add_f32_dpp v137, v137, v137 quad_perm:[1,0,3,2] row_mask:0xf bank_mask:0xf bound_ctrl:1
	v_add_f32_dpp v134, v134, v134 quad_perm:[2,3,0,1] row_mask:0xf bank_mask:0xf bound_ctrl:1
	v_add_f32_dpp v135, v135, v135 quad_perm:[2,3,0,1] row_mask:0xf bank_mask:0xf bound_ctrl:1
	v_add_f32_dpp v136, v136, v136 quad_perm:[2,3,0,1] row_mask:0xf bank_mask:0xf bound_ctrl:1
	v_add_f32_dpp v137, v137, v137 quad_perm:[2,3,0,1] row_mask:0xf bank_mask:0xf bound_ctrl:1
	v_add_f32_dpp v134, v134, v134 row_ror:4 row_mask:0xf bank_mask:0xf bound_ctrl:1
	v_add_f32_dpp v135, v135, v135 row_ror:4 row_mask:0xf bank_mask:0xf bound_ctrl:1
	v_add_f32_dpp v136, v136, v136 row_ror:4 row_mask:0xf bank_mask:0xf bound_ctrl:1
	v_add_f32_dpp v137, v137, v137 row_ror:4 row_mask:0xf bank_mask:0xf bound_ctrl:1
	v_add_f32_dpp v134, v134, v134 row_ror:8 row_mask:0xf bank_mask:0xf bound_ctrl:1
	v_add_f32_dpp v135, v135, v135 row_ror:8 row_mask:0xf bank_mask:0xf bound_ctrl:1
	v_add_f32_dpp v136, v136, v136 row_ror:8 row_mask:0xf bank_mask:0xf bound_ctrl:1
	v_add_f32_dpp v137, v137, v137 row_ror:8 row_mask:0xf bank_mask:0xf bound_ctrl:1
	s_mov_b64 s[34:35], exec
	s_mov_b64 exec, s[2:3]
	global_store_dword v138, v134, s[22:23] offset:512 sc0 sc1
	global_store_dword v138, v135, s[22:23] offset:576 sc0 sc1
	global_store_dword v138, v136, s[22:23] offset:640 sc0 sc1
	global_store_dword v138, v137, s[22:23] offset:704 sc0 sc1
	s_mov_b64 exec, s[34:35]
	s_nop 1
	v_mul_f32_e32 v134, v48, v48
	v_mul_f32_e32 v135, v52, v52
	v_mul_f32_e32 v136, v56, v56
	v_mul_f32_e32 v137, v60, v60
	v_fmac_f32_e32 v134, v49, v49
	v_fmac_f32_e32 v135, v53, v53
	v_fmac_f32_e32 v136, v57, v57
	v_fmac_f32_e32 v137, v61, v61
	v_fmac_f32_e32 v134, v50, v50
	v_fmac_f32_e32 v135, v54, v54
	v_fmac_f32_e32 v136, v58, v58
	v_fmac_f32_e32 v137, v62, v62
	v_fmac_f32_e32 v134, v51, v51
	v_fmac_f32_e32 v135, v55, v55
	v_fmac_f32_e32 v136, v59, v59
	v_fmac_f32_e32 v137, v63, v63
	v_add_f32_dpp v134, v134, v134 quad_perm:[1,0,3,2] row_mask:0xf bank_mask:0xf bound_ctrl:1
	v_add_f32_dpp v135, v135, v135 quad_perm:[1,0,3,2] row_mask:0xf bank_mask:0xf bound_ctrl:1
	v_add_f32_dpp v136, v136, v136 quad_perm:[1,0,3,2] row_mask:0xf bank_mask:0xf bound_ctrl:1
	v_add_f32_dpp v137, v137, v137 quad_perm:[1,0,3,2] row_mask:0xf bank_mask:0xf bound_ctrl:1
	v_add_f32_dpp v134, v134, v134 quad_perm:[2,3,0,1] row_mask:0xf bank_mask:0xf bound_ctrl:1
	v_add_f32_dpp v135, v135, v135 quad_perm:[2,3,0,1] row_mask:0xf bank_mask:0xf bound_ctrl:1
	v_add_f32_dpp v136, v136, v136 quad_perm:[2,3,0,1] row_mask:0xf bank_mask:0xf bound_ctrl:1
	v_add_f32_dpp v137, v137, v137 quad_perm:[2,3,0,1] row_mask:0xf bank_mask:0xf bound_ctrl:1
	v_add_f32_dpp v134, v134, v134 row_ror:4 row_mask:0xf bank_mask:0xf bound_ctrl:1
	v_add_f32_dpp v135, v135, v135 row_ror:4 row_mask:0xf bank_mask:0xf bound_ctrl:1
	v_add_f32_dpp v136, v136, v136 row_ror:4 row_mask:0xf bank_mask:0xf bound_ctrl:1
	v_add_f32_dpp v137, v137, v137 row_ror:4 row_mask:0xf bank_mask:0xf bound_ctrl:1
	v_add_f32_dpp v134, v134, v134 row_ror:8 row_mask:0xf bank_mask:0xf bound_ctrl:1
	v_add_f32_dpp v135, v135, v135 row_ror:8 row_mask:0xf bank_mask:0xf bound_ctrl:1
	v_add_f32_dpp v136, v136, v136 row_ror:8 row_mask:0xf bank_mask:0xf bound_ctrl:1
	v_add_f32_dpp v137, v137, v137 row_ror:8 row_mask:0xf bank_mask:0xf bound_ctrl:1
	s_mov_b64 s[34:35], exec
	s_mov_b64 exec, s[2:3]
	global_store_dword v138, v134, s[22:23] offset:768 sc0 sc1
	global_store_dword v138, v135, s[22:23] offset:832 sc0 sc1
	global_store_dword v138, v136, s[22:23] offset:896 sc0 sc1
	global_store_dword v138, v137, s[22:23] offset:960 sc0 sc1
	s_mov_b64 exec, s[34:35]
	s_nop 1
	s_waitcnt vmcnt(0)
	s_barrier
	v_readlane_b32 s0, v255, 6
	v_readlane_b32 s1, v255, 51
	s_nop 3
	s_cmp_lg_u32 s0, 0
	s_cbranch_scc1 .Lq8_waitdone
	v_mov_b32_e32 v134, 0
	v_mov_b32_e32 v135, 1
	s_lshl_b32 s1, s1, 2
	s_add_u32 s32, s76, s1
	s_addc_u32 s33, s77, 0
	s_mov_b64 s[34:35], exec
	s_mov_b64 exec, 1
	global_atomic_add v134, v135, s[32:33]
	s_mov_b32 s27, 0
; __device__ __forceinline__ unsigned xb_ld(unsigned* p) { return __hip_atomic_load(p, __ATOMIC_RELAXED, __HIP_MEMORY_SCOPE_AGENT); }
; __device__ __forceinline__ unsigned xb_add(unsigned* p, unsigned v) { return __hip_atomic_fetch_add(p, v, __ATOMIC_RELAXED, __HIP_MEMORY_SCOPE_AGENT); }
; #define XB_SPIN(cond, bar) do { unsigned _sp = 0; while (cond) { __builtin_amdgcn_s_sleep(1); \
;     if ((++_sp & 255u) == 0u) { if (xb_ld(&(bar)[XB_TMO])) break; if (_sp > XB_SPIN_CAP) { atomicAdd(&(bar)[XB_TMO], 1u); break; } } } } while (0)
; template <int MODE>
; __device__ void phase_norm(const Params& p, const float* __restrict__ X, const float* __restrict__ gain, const int rep) {
;     ...
;       ss += v[i].x * v[i].x + v[i].y * v[i].y + v[i].z * v[i].z + v[i].w * v[i].w;
;     }
;     ss = wave_sum(ss);
;     float rstd = rsqrtf(ss * (1.0f / 1024.0f) + 1e-6f);
; #pragma unroll
;     for (int i = 0; i < 4; ++i) {
;       float4 gg = *(const float4*)(gain + i * 256 + lane * 4);
; __device__ __forceinline__ void xcd_barrier(const XcdBarrier& b, const int wvs) {
;     ...
;     const unsigned old = xb_add(&bar[XB_XSUB(b.x)], 1u);
;     const unsigned gen = old / nloc;
;     if (old + 1u == (gen + 1u) * nloc) {
;       __builtin_amdgcn_fence(__ATOMIC_RELEASE, "agent");
;       asm volatile("s_waitcnt vmcnt(0)" ::: "memory");
;       const unsigned og = xb_add(&bar[XB_TOP], 1u);
;       const unsigned tg = og / nx;
;       if (og + 1u == (tg + 1u) * nx) xb_add(&bar[XB_TOPGEN], 1u);
;       else XB_SPIN(xb_ld(&bar[XB_TOPGEN]) == tg, bar);
;       __builtin_amdgcn_fence(__ATOMIC_ACQUIRE, "agent");
;       xb_add(&bar[XB_XGEN(b.x)], 1u);
;       asm volatile("s_waitcnt vmcnt(0)" ::: "memory");
;     } else {
;       XB_SPIN(xb_ld(&bar[XB_XGEN(b.x)]) == gen, bar);
.Lq8_spin:
	global_load_dword v136, v134, s[32:33] sc1
	s_waitcnt vmcnt(0)
	v_readfirstlane_b32 s0, v136
	s_nop 1
	s_cmp_ge_u32 s0, 4
	s_cbranch_scc1 .Lq8_spun
	s_sleep 1
	s_add_i32 s27, s27, 1
	s_cmp_lt_u32 s27, 0x100000
	s_cbranch_scc1 .Lq8_spin
.Lq8_spun:
	s_mov_b64 exec, s[34:35]
.Lq8_waitdone:
	s_barrier
	buffer_inv sc1
	global_load_dword v184, v174, s[22:23] sc0 sc1
	global_load_dword v185, v174, s[22:23] offset:256 sc0 sc1
	global_load_dword v186, v174, s[22:23] offset:512 sc0 sc1
	global_load_dword v187, v174, s[22:23] offset:768 sc0 sc1
	global_load_dword v188, v139, s[22:23] sc0 sc1
	global_load_dword v189, v139, s[22:23] offset:256 sc0 sc1
	global_load_dword v190, v139, s[22:23] offset:512 sc0 sc1
	global_load_dword v191, v139, s[22:23] offset:768 sc0 sc1
	v_lshlrev_b32_e32 v130, 4, v195
	v_readlane_b32 s0, v255, 52
	s_nop 3
	s_lshl_b32 s0, s0, 10
	v_add_u32_e32 v130, s0, v130
	global_load_dwordx4 v[130:133], v130, s[28:29]
	s_waitcnt vmcnt(1)
	v_add_f32_dpp v184, v184, v184 quad_perm:[1,0,3,2] row_mask:0xf bank_mask:0xf bound_ctrl:1
	v_add_f32_dpp v185, v185, v185 quad_perm:[1,0,3,2] row_mask:0xf bank_mask:0xf bound_ctrl:1
	v_add_f32_dpp v186, v186, v186 quad_perm:[1,0,3,2] row_mask:0xf bank_mask:0xf bound_ctrl:1
	v_add_f32_dpp v187, v187, v187 quad_perm:[1,0,3,2] row_mask:0xf bank_mask:0xf bound_ctrl:1
	v_add_f32_dpp v188, v188, v188 quad_perm:[1,0,3,2] row_mask:0xf bank_mask:0xf bound_ctrl:1
	v_add_f32_dpp v189, v189, v189 quad_perm:[1,0,3,2] row_mask:0xf bank_mask:0xf bound_ctrl:1
	v_add_f32_dpp v190, v190, v190 quad_perm:[1,0,3,2] row_mask:0xf bank_mask:0xf bound_ctrl:1
	v_add_f32_dpp v191, v191, v191 quad_perm:[1,0,3,2] row_mask:0xf bank_mask:0xf bound_ctrl:1
	v_add_f32_dpp v184, v184, v184 quad_perm:[2,3,0,1] row_mask:0xf bank_mask:0xf bound_ctrl:1
	v_add_f32_dpp v185, v185, v185 quad_perm:[2,3,0,1] row_mask:0xf bank_mask:0xf bound_ctrl:1
	v_add_f32_dpp v186, v186, v186 quad_perm:[2,3,0,1] row_mask:0xf bank_mask:0xf bound_ctrl:1
	v_add_f32_dpp v187, v187, v187 quad_perm:[2,3,0,1] row_mask:0xf bank_mask:0xf bound_ctrl:1
	v_add_f32_dpp v188, v188, v188 quad_perm:[2,3,0,1] row_mask:0xf bank_mask:0xf bound_ctrl:1
	v_add_f32_dpp v189, v189, v189 quad_perm:[2,3,0,1] row_mask:0xf bank_mask:0xf bound_ctrl:1
	v_add_f32_dpp v190, v190, v190 quad_perm:[2,3,0,1] row_mask:0xf bank_mask:0xf bound_ctrl:1
	v_add_f32_dpp v191, v191, v191 quad_perm:[2,3,0,1] row_mask:0xf bank_mask:0xf bound_ctrl:1
	v_add_f32_dpp v184, v184, v184 row_ror:4 row_mask:0xf bank_mask:0xf bound_ctrl:1
	v_add_f32_dpp v185, v185, v185 row_ror:4 row_mask:0xf bank_mask:0xf bound_ctrl:1
	v_add_f32_dpp v186, v186, v186 row_ror:4 row_mask:0xf bank_mask:0xf bound_ctrl:1
	v_add_f32_dpp v187, v187, v187 row_ror:4 row_mask:0xf bank_mask:0xf bound_ctrl:1
	v_add_f32_dpp v188, v188, v188 row_ror:4 row_mask:0xf bank_mask:0xf bound_ctrl:1
	v_add_f32_dpp v189, v189, v189 row_ror:4 row_mask:0xf bank_mask:0xf bound_ctrl:1
	v_add_f32_dpp v190, v190, v190 row_ror:4 row_mask:0xf bank_mask:0xf bound_ctrl:1
	v_add_f32_dpp v191, v191, v191 row_ror:4 row_mask:0xf bank_mask:0xf bound_ctrl:1
	v_add_f32_dpp v184, v184, v184 row_ror:8 row_mask:0xf bank_mask:0xf bound_ctrl:1
	v_add_f32_dpp v185, v185, v185 row_ror:8 row_mask:0xf bank_mask:0xf bound_ctrl:1
	v_add_f32_dpp v186, v186, v186 row_ror:8 row_mask:0xf bank_mask:0xf bound_ctrl:1
	v_add_f32_dpp v187, v187, v187 row_ror:8 row_mask:0xf bank_mask:0xf bound_ctrl:1
	v_add_f32_dpp v188, v188, v188 row_ror:8 row_mask:0xf bank_mask:0xf bound_ctrl:1
	v_add_f32_dpp v189, v189, v189 row_ror:8 row_mask:0xf bank_mask:0xf bound_ctrl:1
	v_add_f32_dpp v190, v190, v190 row_ror:8 row_mask:0xf bank_mask:0xf bound_ctrl:1
	v_add_f32_dpp v191, v191, v191 row_ror:8 row_mask:0xf bank_mask:0xf bound_ctrl:1
	v_mov_b32_e32 v196, 0x358637bd
	v_mov_b32_e32 v197, 0x358637bd
	v_mov_b32_e32 v198, 0x358637bd
	v_mov_b32_e32 v199, 0x358637bd
	v_mov_b32_e32 v200, 0x358637bd
	v_mov_b32_e32 v201, 0x358637bd
	v_mov_b32_e32 v202, 0x358637bd
	v_mov_b32_e32 v203, 0x358637bd
	v_fmac_f32_e32 v196, 0x3a800000, v184
	v_fmac_f32_e32 v197, 0x3a800000, v185
	v_fmac_f32_e32 v198, 0x3a800000, v186
	v_fmac_f32_e32 v199, 0x3a800000, v187
	v_fmac_f32_e32 v200, 0x3a800000, v188
	v_fmac_f32_e32 v201, 0x3a800000, v189
	v_fmac_f32_e32 v202, 0x3a800000, v190
	v_fmac_f32_e32 v203, 0x3a800000, v191
	v_rsq_f32_e32 v196, v196
	v_rsq_f32_e32 v197, v197
	v_rsq_f32_e32 v198, v198
	v_rsq_f32_e32 v199, v199
	v_rsq_f32_e32 v200, v200
	v_rsq_f32_e32 v201, v201
	v_rsq_f32_e32 v202, v202
	v_rsq_f32_e32 v203, v203
	s_nop 1
	v_readlane_b32 s36, v196, 0
	v_readlane_b32 s37, v196, 16
	v_readlane_b32 s38, v196, 32
	v_readlane_b32 s39, v196, 48
	v_readlane_b32 s40, v197, 0
	v_readlane_b32 s41, v197, 16
	v_readlane_b32 s42, v197, 32
	v_readlane_b32 s43, v197, 48
	v_readlane_b32 s44, v198, 0
	v_readlane_b32 s45, v198, 16
	v_readlane_b32 s46, v198, 32
	v_readlane_b32 s47, v198, 48
	v_readlane_b32 s48, v199, 0
	v_readlane_b32 s49, v199, 16
	v_readlane_b32 s50, v199, 32
	v_readlane_b32 s51, v199, 48
	v_readlane_b32 s52, v200, 0
	v_readlane_b32 s53, v200, 16
	v_readlane_b32 s54, v200, 32
	v_readlane_b32 s55, v200, 48
	v_readlane_b32 s56, v201, 0
	v_readlane_b32 s57, v201, 16
	v_readlane_b32 s58, v201, 32
	v_readlane_b32 s59, v201, 48
	v_readlane_b32 s60, v202, 0
	v_readlane_b32 s61, v202, 16
	v_readlane_b32 s62, v202, 32
	v_readlane_b32 s63, v202, 48
	v_readlane_b32 s64, v203, 0
	v_readlane_b32 s65, v203, 16
	v_readlane_b32 s66, v203, 32
	v_readlane_b32 s67, v203, 48
	s_waitcnt vmcnt(0)
; template <int MODE>
; __device__ void phase_norm(const Params& p, const float* __restrict__ X, const float* __restrict__ gain, const int rep) {
;     ...
; #pragma unroll
;     for (int i = 0; i < 4; ++i) {
;       float4 gg = *(const float4*)(gain + i * 256 + lane * 4);
;       if (MODE == 0) {
;         u32x2 o;
;         o.x = pack2(v[i].x * rstd * gg.x, v[i].y * rstd * gg.y);
;         o.y = pack2(v[i].z * rstd * gg.z, v[i].w * rstd * gg.w);
;         *(u32x2*)(H + (size_t)row * 1024 + i * 256 + lane * 4) = o;
;       } else {
;         float4 o = make_float4(v[i].x * rstd * gg.x, v[i].y * rstd * gg.y, v[i].z * rstd * gg.z, v[i].w * rstd * gg.w);
;         *(float4*)(p.out + OUT_Y + (size_t)row * 1024 + i * 256 + lane * 4) = o;
;       }
	s_nop 1
	v_subrev_u32_e32 v182, 0x80000, v181
	v_mul_f32_e32 v64, s36, v64
	v_mul_f32_e32 v65, s36, v65
	v_mul_f32_e32 v66, s36, v66
	v_mul_f32_e32 v67, s36, v67
	v_mul_f32_e32 v64, v64, v130
	v_mul_f32_e32 v65, v65, v131
	v_mul_f32_e32 v66, v66, v132
	v_mul_f32_e32 v67, v67, v133
	global_store_dwordx4 v182, v[64:67], s[24:25]
	v_mul_f32_e32 v68, s37, v68
	v_mul_f32_e32 v69, s37, v69
	v_mul_f32_e32 v70, s37, v70
	v_mul_f32_e32 v71, s37, v71
	v_mul_f32_e32 v68, v68, v130
	v_mul_f32_e32 v69, v69, v131
	v_mul_f32_e32 v70, v70, v132
	v_mul_f32_e32 v71, v71, v133
	v_add_u32_e32 v182, 0x1000, v182
	global_store_dwordx4 v182, v[68:71], s[24:25]
	v_mul_f32_e32 v72, s38, v72
	v_mul_f32_e32 v73, s38, v73
	v_mul_f32_e32 v74, s38, v74
	v_mul_f32_e32 v75, s38, v75
	v_mul_f32_e32 v72, v72, v130
	v_mul_f32_e32 v73, v73, v131
	v_mul_f32_e32 v74, v74, v132
	v_mul_f32_e32 v75, v75, v133
	v_add_u32_e32 v182, 0x1000, v182
	global_store_dwordx4 v182, v[72:75], s[24:25]
	v_mul_f32_e32 v76, s39, v76
	v_mul_f32_e32 v77, s39, v77
	v_mul_f32_e32 v78, s39, v78
	v_mul_f32_e32 v79, s39, v79
	v_mul_f32_e32 v76, v76, v130
	v_mul_f32_e32 v77, v77, v131
	v_mul_f32_e32 v78, v78, v132
	v_mul_f32_e32 v79, v79, v133
	v_add_u32_e32 v182, 0x1000, v182
	global_store_dwordx4 v182, v[76:79], s[24:25]
	v_mul_f32_e32 v80, s40, v80
	v_mul_f32_e32 v81, s40, v81
	v_mul_f32_e32 v82, s40, v82
	v_mul_f32_e32 v83, s40, v83
	v_mul_f32_e32 v80, v80, v130
	v_mul_f32_e32 v81, v81, v131
	v_mul_f32_e32 v82, v82, v132
	v_mul_f32_e32 v83, v83, v133
	v_add_u32_e32 v182, 0x1000, v182
	global_store_dwordx4 v182, v[80:83], s[24:25]
	v_mul_f32_e32 v84, s41, v84
	v_mul_f32_e32 v85, s41, v85
	v_mul_f32_e32 v86, s41, v86
	v_mul_f32_e32 v87, s41, v87
	v_mul_f32_e32 v84, v84, v130
	v_mul_f32_e32 v85, v85, v131
	v_mul_f32_e32 v86, v86, v132
	v_mul_f32_e32 v87, v87, v133
	v_add_u32_e32 v182, 0x1000, v182
	global_store_dwordx4 v182, v[84:87], s[24:25]
	v_mul_f32_e32 v88, s42, v88
	v_mul_f32_e32 v89, s42, v89
	v_mul_f32_e32 v90, s42, v90
	v_mul_f32_e32 v91, s42, v91
	v_mul_f32_e32 v88, v88, v130
	v_mul_f32_e32 v89, v89, v131
	v_mul_f32_e32 v90, v90, v132
	v_mul_f32_e32 v91, v91, v133
	v_add_u32_e32 v182, 0x1000, v182
	global_store_dwordx4 v182, v[88:91], s[24:25]
	v_mul_f32_e32 v92, s43, v92
	v_mul_f32_e32 v93, s43, v93
	v_mul_f32_e32 v94, s43, v94
	v_mul_f32_e32 v95, s43, v95
	v_mul_f32_e32 v92, v92, v130
	v_mul_f32_e32 v93, v93, v131
	v_mul_f32_e32 v94, v94, v132
	v_mul_f32_e32 v95, v95, v133
	v_add_u32_e32 v182, 0x1000, v182
	global_store_dwordx4 v182, v[92:95], s[24:25]
	v_mul_f32_e32 v96, s44, v96
	v_mul_f32_e32 v97, s44, v97
	v_mul_f32_e32 v98, s44, v98
	v_mul_f32_e32 v99, s44, v99
	v_mul_f32_e32 v96, v96, v130
	v_mul_f32_e32 v97, v97, v131
	v_mul_f32_e32 v98, v98, v132
	v_mul_f32_e32 v99, v99, v133
	v_add_u32_e32 v182, 0x1000, v182
	global_store_dwordx4 v182, v[96:99], s[24:25]
	v_mul_f32_e32 v100, s45, v100
	v_mul_f32_e32 v101, s45, v101
	v_mul_f32_e32 v102, s45, v102
	v_mul_f32_e32 v103, s45, v103
	v_mul_f32_e32 v100, v100, v130
	v_mul_f32_e32 v101, v101, v131
	v_mul_f32_e32 v102, v102, v132
	v_mul_f32_e32 v103, v103, v133
	v_add_u32_e32 v182, 0x1000, v182
	global_store_dwordx4 v182, v[100:103], s[24:25]
	v_mul_f32_e32 v104, s46, v104
	v_mul_f32_e32 v105, s46, v105
	v_mul_f32_e32 v106, s46, v106
	v_mul_f32_e32 v107, s46, v107
	v_mul_f32_e32 v104, v104, v130
	v_mul_f32_e32 v105, v105, v131
	v_mul_f32_e32 v106, v106, v132
	v_mul_f32_e32 v107, v107, v133
	v_add_u32_e32 v182, 0x1000, v182
	global_store_dwordx4 v182, v[104:107], s[24:25]
	v_mul_f32_e32 v108, s47, v108
	v_mul_f32_e32 v109, s47, v109
	v_mul_f32_e32 v110, s47, v110
	v_mul_f32_e32 v111, s47, v111
	v_mul_f32_e32 v108, v108, v130
	v_mul_f32_e32 v109, v109, v131
	v_mul_f32_e32 v110, v110, v132
	v_mul_f32_e32 v111, v111, v133
	v_add_u32_e32 v182, 0x1000, v182
	global_store_dwordx4 v182, v[108:111], s[24:25]
	v_mul_f32_e32 v112, s48, v112
	v_mul_f32_e32 v113, s48, v113
	v_mul_f32_e32 v114, s48, v114
	v_mul_f32_e32 v115, s48, v115
	v_mul_f32_e32 v112, v112, v130
	v_mul_f32_e32 v113, v113, v131
	v_mul_f32_e32 v114, v114, v132
	v_mul_f32_e32 v115, v115, v133
	v_add_u32_e32 v182, 0x1000, v182
	global_store_dwordx4 v182, v[112:115], s[24:25]
	v_mul_f32_e32 v116, s49, v116
	v_mul_f32_e32 v117, s49, v117
	v_mul_f32_e32 v118, s49, v118
	v_mul_f32_e32 v119, s49, v119
	v_mul_f32_e32 v116, v116, v130
	v_mul_f32_e32 v117, v117, v131
	v_mul_f32_e32 v118, v118, v132
	v_mul_f32_e32 v119, v119, v133
	v_add_u32_e32 v182, 0x1000, v182
	global_store_dwordx4 v182, v[116:119], s[24:25]
	v_mul_f32_e32 v120, s50, v120
	v_mul_f32_e32 v121, s50, v121
	v_mul_f32_e32 v122, s50, v122
	v_mul_f32_e32 v123, s50, v123
	v_mul_f32_e32 v120, v120, v130
	v_mul_f32_e32 v121, v121, v131
	v_mul_f32_e32 v122, v122, v132
	v_mul_f32_e32 v123, v123, v133
	v_add_u32_e32 v182, 0x1000, v182
	global_store_dwordx4 v182, v[120:123], s[24:25]
	v_mul_f32_e32 v124, s51, v124
	v_mul_f32_e32 v125, s51, v125
	v_mul_f32_e32 v126, s51, v126
	v_mul_f32_e32 v127, s51, v127
	v_mul_f32_e32 v124, v124, v130
	v_mul_f32_e32 v125, v125, v131
	v_mul_f32_e32 v126, v126, v132
	v_mul_f32_e32 v127, v127, v133
	v_add_u32_e32 v182, 0x1000, v182
	global_store_dwordx4 v182, v[124:127], s[24:25]
	v_mov_b32_e32 v182, v181
	v_mul_f32_e32 v0, s52, v0
	v_mul_f32_e32 v1, s52, v1
	v_mul_f32_e32 v2, s52, v2
	v_mul_f32_e32 v3, s52, v3
	v_mul_f32_e32 v0, v0, v130
	v_mul_f32_e32 v1, v1, v131
	v_mul_f32_e32 v2, v2, v132
	v_mul_f32_e32 v3, v3, v133
; template <int MODE>
; __device__ void phase_norm(const Params& p, const float* __restrict__ X, const float* __restrict__ gain, const int rep) {
;     ...
; #pragma unroll
;     for (int i = 0; i < 4; ++i) {
;       float4 gg = *(const float4*)(gain + i * 256 + lane * 4);
;       if (MODE == 0) {
;         u32x2 o;
;         o.x = pack2(v[i].x * rstd * gg.x, v[i].y * rstd * gg.y);
;         o.y = pack2(v[i].z * rstd * gg.z, v[i].w * rstd * gg.w);
;         *(u32x2*)(H + (size_t)row * 1024 + i * 256 + lane * 4) = o;
;       } else {
;         float4 o = make_float4(v[i].x * rstd * gg.x, v[i].y * rstd * gg.y, v[i].z * rstd * gg.z, v[i].w * rstd * gg.w);
;         *(float4*)(p.out + OUT_Y + (size_t)row * 1024 + i * 256 + lane * 4) = o;
;       }
; template <int NH>
; __device__ void gemm_sample_rows(const Params& p, const u16* __restrict__ A, const u16* __restrict__ Bt,
;                                  const float* __restrict__ resid, float* __restrict__ outf, unsigned char* smem, const int rep) {
;   constexpr int K = 2048, RS = 65;
;   float* red = (float*)smem;
;   float* rstdS = red + 8 * 64 * RS;
;   const int tid = (int)p.tidx, lane = tid & 63, w = (int)p.wv, l15 = lane & 15, g = lane >> 4;
;   const float* parts = (const float*)(p.ws + OFF_PARTS);
;   for (int item0 = blockIdx.x; item0 < 256 * rep; item0 += gridDim.x) {
;     const int item = item0 & 255;
;     const int m0 = NPROMPT + (item >> 4) * 64, n0 = (item & 15) * 64;
;     for (int idx = tid; idx < 64 * NH; idx += NTHR) {
	global_store_dwordx4 v182, v[0:3], s[24:25]
	v_mul_f32_e32 v4, s53, v4
	v_mul_f32_e32 v5, s53, v5
	v_mul_f32_e32 v6, s53, v6
	v_mul_f32_e32 v7, s53, v7
	v_mul_f32_e32 v4, v4, v130
	v_mul_f32_e32 v5, v5, v131
	v_mul_f32_e32 v6, v6, v132
	v_mul_f32_e32 v7, v7, v133
	v_add_u32_e32 v182, 0x1000, v182
	global_store_dwordx4 v182, v[4:7], s[24:25]
	v_mul_f32_e32 v8, s54, v8
	v_mul_f32_e32 v9, s54, v9
	v_mul_f32_e32 v10, s54, v10
	v_mul_f32_e32 v11, s54, v11
	v_mul_f32_e32 v8, v8, v130
	v_mul_f32_e32 v9, v9, v131
	v_mul_f32_e32 v10, v10, v132
	v_mul_f32_e32 v11, v11, v133
	v_add_u32_e32 v182, 0x1000, v182
	global_store_dwordx4 v182, v[8:11], s[24:25]
	v_mul_f32_e32 v12, s55, v12
	v_mul_f32_e32 v13, s55, v13
	v_mul_f32_e32 v14, s55, v14
	v_mul_f32_e32 v15, s55, v15
	v_mul_f32_e32 v12, v12, v130
	v_mul_f32_e32 v13, v13, v131
	v_mul_f32_e32 v14, v14, v132
	v_mul_f32_e32 v15, v15, v133
	v_add_u32_e32 v182, 0x1000, v182
	global_store_dwordx4 v182, v[12:15], s[24:25]
	v_mul_f32_e32 v16, s56, v16
	v_mul_f32_e32 v17, s56, v17
	v_mul_f32_e32 v18, s56, v18
	v_mul_f32_e32 v19, s56, v19
	v_mul_f32_e32 v16, v16, v130
	v_mul_f32_e32 v17, v17, v131
	v_mul_f32_e32 v18, v18, v132
	v_mul_f32_e32 v19, v19, v133
	v_add_u32_e32 v182, 0x1000, v182
	global_store_dwordx4 v182, v[16:19], s[24:25]
	v_mul_f32_e32 v20, s57, v20
	v_mul_f32_e32 v21, s57, v21
	v_mul_f32_e32 v22, s57, v22
	v_mul_f32_e32 v23, s57, v23
	v_mul_f32_e32 v20, v20, v130
	v_mul_f32_e32 v21, v21, v131
	v_mul_f32_e32 v22, v22, v132
	v_mul_f32_e32 v23, v23, v133
	v_add_u32_e32 v182, 0x1000, v182
	global_store_dwordx4 v182, v[20:23], s[24:25]
	v_mul_f32_e32 v24, s58, v24
	v_mul_f32_e32 v25, s58, v25
	v_mul_f32_e32 v26, s58, v26
	v_mul_f32_e32 v27, s58, v27
	v_mul_f32_e32 v24, v24, v130
	v_mul_f32_e32 v25, v25, v131
	v_mul_f32_e32 v26, v26, v132
	v_mul_f32_e32 v27, v27, v133
	v_add_u32_e32 v182, 0x1000, v182
	global_store_dwordx4 v182, v[24:27], s[24:25]
	v_mul_f32_e32 v28, s59, v28
	v_mul_f32_e32 v29, s59, v29
	v_mul_f32_e32 v30, s59, v30
	v_mul_f32_e32 v31, s59, v31
	v_mul_f32_e32 v28, v28, v130
	v_mul_f32_e32 v29, v29, v131
	v_mul_f32_e32 v30, v30, v132
	v_mul_f32_e32 v31, v31, v133
	v_add_u32_e32 v182, 0x1000, v182
	global_store_dwordx4 v182, v[28:31], s[24:25]
	v_mul_f32_e32 v32, s60, v32
	v_mul_f32_e32 v33, s60, v33
	v_mul_f32_e32 v34, s60, v34
	v_mul_f32_e32 v35, s60, v35
	v_mul_f32_e32 v32, v32, v130
	v_mul_f32_e32 v33, v33, v131
	v_mul_f32_e32 v34, v34, v132
	v_mul_f32_e32 v35, v35, v133
	v_add_u32_e32 v182, 0x1000, v182
	global_store_dwordx4 v182, v[32:35], s[24:25]
	v_mul_f32_e32 v36, s61, v36
	v_mul_f32_e32 v37, s61, v37
	v_mul_f32_e32 v38, s61, v38
	v_mul_f32_e32 v39, s61, v39
	v_mul_f32_e32 v36, v36, v130
	v_mul_f32_e32 v37, v37, v131
	v_mul_f32_e32 v38, v38, v132
	v_mul_f32_e32 v39, v39, v133
	v_add_u32_e32 v182, 0x1000, v182
	global_store_dwordx4 v182, v[36:39], s[24:25]
	v_mul_f32_e32 v40, s62, v40
	v_mul_f32_e32 v41, s62, v41
	v_mul_f32_e32 v42, s62, v42
	v_mul_f32_e32 v43, s62, v43
	v_mul_f32_e32 v40, v40, v130
	v_mul_f32_e32 v41, v41, v131
	v_mul_f32_e32 v42, v42, v132
	v_mul_f32_e32 v43, v43, v133
	v_add_u32_e32 v182, 0x1000, v182
	global_store_dwordx4 v182, v[40:43], s[24:25]
	v_mul_f32_e32 v44, s63, v44
	v_mul_f32_e32 v45, s63, v45
	v_mul_f32_e32 v46, s63, v46
	v_mul_f32_e32 v47, s63, v47
	v_mul_f32_e32 v44, v44, v130
	v_mul_f32_e32 v45, v45, v131
	v_mul_f32_e32 v46, v46, v132
	v_mul_f32_e32 v47, v47, v133
	v_add_u32_e32 v182, 0x1000, v182
	global_store_dwordx4 v182, v[44:47], s[24:25]
	v_mul_f32_e32 v48, s64, v48
	v_mul_f32_e32 v49, s64, v49
	v_mul_f32_e32 v50, s64, v50
	v_mul_f32_e32 v51, s64, v51
	v_mul_f32_e32 v48, v48, v130
	v_mul_f32_e32 v49, v49, v131
	v_mul_f32_e32 v50, v50, v132
	v_mul_f32_e32 v51, v51, v133
	v_add_u32_e32 v182, 0x1000, v182
	global_store_dwordx4 v182, v[48:51], s[24:25]
	v_mul_f32_e32 v52, s65, v52
	v_mul_f32_e32 v53, s65, v53
	v_mul_f32_e32 v54, s65, v54
	v_mul_f32_e32 v55, s65, v55
	v_mul_f32_e32 v52, v52, v130
	v_mul_f32_e32 v53, v53, v131
	v_mul_f32_e32 v54, v54, v132
	v_mul_f32_e32 v55, v55, v133
	v_add_u32_e32 v182, 0x1000, v182
	global_store_dwordx4 v182, v[52:55], s[24:25]
	v_mul_f32_e32 v56, s66, v56
	v_mul_f32_e32 v57, s66, v57
	v_mul_f32_e32 v58, s66, v58
	v_mul_f32_e32 v59, s66, v59
	v_mul_f32_e32 v56, v56, v130
	v_mul_f32_e32 v57, v57, v131
	v_mul_f32_e32 v58, v58, v132
	v_mul_f32_e32 v59, v59, v133
	v_add_u32_e32 v182, 0x1000, v182
	global_store_dwordx4 v182, v[56:59], s[24:25]
	v_mul_f32_e32 v60, s67, v60
	v_mul_f32_e32 v61, s67, v61
	v_mul_f32_e32 v62, s67, v62
	v_mul_f32_e32 v63, s67, v63
	v_mul_f32_e32 v60, v60, v130
	v_mul_f32_e32 v61, v61, v131
	v_mul_f32_e32 v62, v62, v132
	v_mul_f32_e32 v63, v63, v133
	v_add_u32_e32 v182, 0x1000, v182
	global_store_dwordx4 v182, v[60:63], s[24:25]
	s_waitcnt vmcnt(0)
	s_barrier
	s_mov_b64 s[0:1], 0
	s_add_u32 s12, s84, s0
	s_addc_u32 s13, s85, s1
	v_readlane_b32 s21, v255, 6
	s_bfe_u32 s22, s90, 0x10008
	s_lshl_b32 s20, s21, 6
	s_add_i32 s22, s22, 1
	s_add_u32 s6, s12, 0x15aa2000
	s_addc_u32 s7, s13, 0
	s_add_u32 s8, s12, 0x19ea2000
	s_addc_u32 s9, s13, 0
	s_waitcnt vmcnt(1)
	v_mbcnt_lo_u32_b32 v0, -1, 0
	s_add_u32 s10, s12, 0x15662000
	v_mbcnt_hi_u32_b32 v195, -1, v0
	s_addc_u32 s11, s13, 0
	s_lshl_b32 s23, s22, 9
	s_mov_b32 s23, 0
	s_mov_b64 s[2:3], 0
	v_add_u32_e32 v196, s20, v195
	s_cmp_lt_i32 s78, s23
	v_and_b32_e32 v181, 15, v195
	s_cbranch_scc1 .LBB0_2008
	v_and_b32_e32 v0, 15, v195
	s_branch .LBB0_2009

; template <int MODE>
; __device__ void phase_norm(const Params& p, const float* __restrict__ X, const float* __restrict__ gain, const int rep) {
;   const int tid = (int)p.tidx, lane = tid & 63, w = (int)p.wv;
;   u16* H = (u16*)(p.ws + OFF_H);
;   for (int row0 = blockIdx.x * 8 + w; row0 < T_TOK * rep; row0 += gridDim.x * 8) {
;     const int row = row0 % T_TOK;
;     const float* xr = X + (size_t)row * 1024;
;     float4 v[4];
;     float ss = 0.f;
; #pragma unroll
;     for (int i = 0; i < 4; ++i) {
;       v[i] = *(const float4*)(xr + i * 256 + lane * 4);
;       ss += v[i].x * v[i].x + v[i].y * v[i].y + v[i].z * v[i].z + v[i].w * v[i].w;
;     }
;     ss = wave_sum(ss);
;     float rstd = rsqrtf(ss * (1.0f / 1024.0f) + 1e-6f);
; #pragma unroll
;     for (int i = 0; i < 4; ++i) {
;       float4 gg = *(const float4*)(gain + i * 256 + lane * 4);
; template <int PH>
; __device__ __forceinline__ void run_phase(Params p, unsigned char* smem, const int wvs) {
;     ...
;   if (PH == 9) phase_norm<1>(p, (const float*)(p.ws + OFF_X2), p.final_norm, rep);
.LBB0_2196:
	s_cmp_lt_i32 s86, 10
	s_cselect_b64 s[0:1], -1, 0
	s_cmp_gt_i32 s88, 8
	s_cselect_b64 s[2:3], -1, 0
	s_and_b64 s[0:1], s[0:1], s[2:3]
	s_andn2_b64 vcc, exec, s[0:1]
	s_cbranch_vccnz .LBB0_2359
	s_mov_b64 s[0:1], 0
	v_readlane_b32 s2, v255, 6
	s_lshl_b32 s3, s78, 3
	s_add_i32 s2, s2, s3
	s_addk_i32 s2, 0x4000
	s_and_b32 s4, s90, 0x200
	s_mov_b32 s5, 0
	s_cmp_eq_u64 s[4:5], 0
	s_movk_i32 s3, 0x4400
	s_cselect_b32 s3, s3, 0x8800
	s_cmp_ge_i32 s2, s3
	s_cbranch_scc1 .LBB0_2200
	v_readlane_b32 s8, v255, 0
	v_readlane_b32 s9, v255, 1
	s_load_dwordx4 s[4:7], s[8:9], 0x90
	s_waitcnt vmcnt(1)
	v_mbcnt_lo_u32_b32 v0, -1, 0
	v_mbcnt_hi_u32_b32 v25, -1, v0
	v_lshlrev_b32_e32 v0, 4, v25
	v_and_b32_e32 v18, 0x3f0, v0
	s_waitcnt lgkmcnt(0)
	global_load_dwordx4 v[0:3], v18, s[4:5]
	global_load_dwordx4 v[4:7], v18, s[4:5] offset:1024
	global_load_dwordx4 v[8:11], v18, s[4:5] offset:2048
	global_load_dwordx4 v[12:15], v18, s[4:5] offset:3072
	s_waitcnt vmcnt(4)
	v_and_b32_e32 v20, 64, v25
	v_add_u32_e32 v26, 64, v20
	v_xor_b32_e32 v20, 32, v25
	v_cmp_lt_i32_e32 vcc, v20, v26
	v_xor_b32_e32 v21, 16, v25
	s_lshl_b64 s[4:5], s[0:1], 2
	v_cndmask_b32_e32 v20, v25, v20, vcc
	v_cmp_lt_i32_e32 vcc, v21, v26
	v_xor_b32_e32 v22, 8, v25
	s_add_u32 s6, s6, s4
	v_cndmask_b32_e32 v21, v25, v21, vcc
	v_cmp_lt_i32_e32 vcc, v22, v26
	v_xor_b32_e32 v23, 4, v25
	s_addc_u32 s7, s7, s5
	v_cndmask_b32_e32 v22, v25, v22, vcc
	v_cmp_lt_i32_e32 vcc, v23, v26
	v_xor_b32_e32 v24, 2, v25
	s_add_u32 s0, s84, s0
	v_cndmask_b32_e32 v23, v25, v23, vcc
	v_cmp_lt_i32_e32 vcc, v24, v26
	v_xor_b32_e32 v27, 1, v25
	s_addc_u32 s1, s85, s1
	v_mov_b32_e32 v19, 0
	v_cndmask_b32_e32 v24, v25, v24, vcc
	v_cmp_lt_i32_e32 vcc, v27, v26
	v_lshl_add_u64 v[16:17], s[0:1], 0, v[18:19]
	s_mov_b64 s[0:1], 0x19ea2000
	v_cndmask_b32_e32 v25, v25, v27, vcc
	v_lshl_add_u64 v[16:17], v[16:17], 0, s[0:1]
	v_lshlrev_b32_e32 v20, 2, v20
	v_lshlrev_b32_e32 v21, 2, v21
	v_lshlrev_b32_e32 v22, 2, v22
	v_lshlrev_b32_e32 v23, 2, v23
	v_lshlrev_b32_e32 v24, 2, v24
	v_lshlrev_b32_e32 v25, 2, v25
	s_lshl_b32 s4, s96, 3
	v_lshl_add_u64 v[18:19], s[6:7], 0, v[18:19]
	v_mov_b32_e32 v26, 0x358637bd
	s_mov_b32 s5, 0x800000
